# baseline (speedup 1.0000x reference)
; __device__ __forceinline__ float shfl_idx(float v, int srclane) { return __int_as_float(__builtin_amdgcn_ds_bpermute(srclane << 2, __float_as_int(v))); }
; __device__ __forceinline__ int crow(int r, int hi) { return (r & 3) + 8 * (r >> 2) + 4 * hi; }
; __device__ __forceinline__ void dil_wave_item(const bf16* __restrict__ qkv, bf16* __restrict__ odil, float* __restrict__ lse,
;                               int pat, int g  , int head, char* wl  , const int W) {
;     ...
;   const float rl = __builtin_amdgcn_rcpf(ls);
; #pragma unroll
;   for (int r = 0; r < 16; ++r) {
;     const int q = crow(r, hi);
;     const float rq = shfl_idx(rl, q);
;     bf16* dst = odil + ((size_t)pat * T + tbase + (i0 + q) * dil) * 512 + head * 64 + r32;
;     dst[0] = __float2bfloat16(o0[r] * rq); dst[32] = __float2bfloat16(o1[r] * rq);
;   }
.LBB0_82:
	s_or_b64 exec, exec, s[4:5]
	v_rcp_f32_e32 v38, v35
	v_or_b32_e32 v36, s78, v91
	v_lshlrev_b32_e32 v36, s71, v36
	v_ashrrev_i32_e32 v37, 31, v36
	v_lshl_add_u64 v[36:37], v[32:33], 0, v[36:37]
	v_lshlrev_b32_e32 v34, 1, v90
	v_mov_b32_e32 v35, v83
	v_lshlrev_b64 v[36:37], 10, v[36:37]
	v_lshl_add_u64 v[34:35], s[76:77], 0, v[34:35]
	s_add_i32 s70, s70, s33
	v_lshl_add_u64 v[36:37], v[34:35], 0, v[36:37]
	v_pk_mul_f32 v[0:1], v[0:1], v[38:39] op_sel_hi:[1,0]
	v_pk_mul_f32 v[2:3], v[2:3], v[38:39] op_sel_hi:[1,0]
	v_cvt_pk_bf16_f32 v0, v0, v1
	v_cvt_pk_bf16_f32 v1, v2, v3
	global_store_dwordx2 v[36:37], v[0:1], off
	v_pk_mul_f32 v[4:5], v[4:5], v[38:39] op_sel_hi:[1,0]
	v_pk_mul_f32 v[6:7], v[6:7], v[38:39] op_sel_hi:[1,0]
	v_cvt_pk_bf16_f32 v4, v4, v5
	v_cvt_pk_bf16_f32 v5, v6, v7
	global_store_dwordx2 v[36:37], v[4:5], off offset:16
	v_pk_mul_f32 v[8:9], v[8:9], v[38:39] op_sel_hi:[1,0]
	v_pk_mul_f32 v[10:11], v[10:11], v[38:39] op_sel_hi:[1,0]
	v_cvt_pk_bf16_f32 v8, v8, v9
	v_cvt_pk_bf16_f32 v9, v10, v11
	global_store_dwordx2 v[36:37], v[8:9], off offset:32
	v_pk_mul_f32 v[12:13], v[12:13], v[38:39] op_sel_hi:[1,0]
	v_pk_mul_f32 v[14:15], v[14:15], v[38:39] op_sel_hi:[1,0]
	v_cvt_pk_bf16_f32 v12, v12, v13
	v_cvt_pk_bf16_f32 v13, v14, v15
	global_store_dwordx2 v[36:37], v[12:13], off offset:48
	v_pk_mul_f32 v[16:17], v[16:17], v[38:39] op_sel_hi:[1,0]
	v_pk_mul_f32 v[18:19], v[18:19], v[38:39] op_sel_hi:[1,0]
	v_cvt_pk_bf16_f32 v16, v16, v17
	v_cvt_pk_bf16_f32 v17, v18, v19
	global_store_dwordx2 v[36:37], v[16:17], off offset:64
	v_pk_mul_f32 v[20:21], v[20:21], v[38:39] op_sel_hi:[1,0]
	v_pk_mul_f32 v[22:23], v[22:23], v[38:39] op_sel_hi:[1,0]
	v_cvt_pk_bf16_f32 v20, v20, v21
	v_cvt_pk_bf16_f32 v21, v22, v23
	global_store_dwordx2 v[36:37], v[20:21], off offset:80
	v_pk_mul_f32 v[24:25], v[24:25], v[38:39] op_sel_hi:[1,0]
	v_pk_mul_f32 v[26:27], v[26:27], v[38:39] op_sel_hi:[1,0]
	v_cvt_pk_bf16_f32 v24, v24, v25
	v_cvt_pk_bf16_f32 v25, v26, v27
	global_store_dwordx2 v[36:37], v[24:25], off offset:96
	v_pk_mul_f32 v[28:29], v[28:29], v[38:39] op_sel_hi:[1,0]
	v_pk_mul_f32 v[30:31], v[30:31], v[38:39] op_sel_hi:[1,0]
	v_cvt_pk_bf16_f32 v28, v28, v29
	v_cvt_pk_bf16_f32 v29, v30, v31
	global_store_dwordx2 v[36:37], v[28:29], off offset:112
	s_cmpk_gt_i32 s70, 0xbff
	s_cbranch_scc1 .LBB0_94

; #define otid() (W * 64 + olane())
; __device__ __forceinline__ void dil_wave_item(const bf16* __restrict__ qkv, bf16* __restrict__ odil, float* __restrict__ lse,
;                               int pat, int g  , int head, char* wl  , const int W) {
;   const int lane = otid() & 63, r32 = lane & 31, hi = lane >> 5;
;   const int dil = (pat == 0) ? 1 : (pat == 1 ? 4 : 16);
;   int seq0, slen, gl;
;   if (g < 256) { seq0 = 0; slen = 8192; gl = g; } else if (g < 512) { seq0 = 8192; slen = 8192; gl = g - 256; } else { seq0 = 16384; slen = 16384; gl = g - 512; }
;   const int L = slen / dil, tpr = L / 32, res = gl / tpr, i0 = (gl % tpr) * 32;
;   const int tbase = seq0 + res;
;   bf16x8 qr[4];
;   { const bf16* qp = qkv + (size_t)(tbase + (i0 + r32) * dil) * LDQ + 1536 + head * 64 + hi * 8;
; #pragma unroll
;     for (int d0 = 0; d0 < 4; ++d0) qr[d0] = *reinterpret_cast<const bf16x8*>(qp + d0 * 16); }
;   f32x16 sc[5];
; #pragma unroll
;   for (int kb = 0; kb < 5; ++kb) {
;     int kc = i0 - 64 + kb * 32 + r32; kc = min(max(kc, 0), L - 1);
;     const bf16* kp = qkv + (size_t)(tbase + kc * dil) * LDQ + 2048 + head * 64 + hi * 8;
;     f32x16 a = {};
; #pragma unroll
;     for (int d0 = 0; d0 < 4; ++d0) {
;       bf16x8 kf = *reinterpret_cast<const bf16x8*>(kp + d0 * 16);
;       a = __builtin_amdgcn_mfma_f32_32x32x16_bf16(kf, qr[d0], a, 0, 0, 0);
;     }
;     sc[kb] = a;
.LBB0_90:
	s_add_i32 s7, s70, 0x3ff
	s_and_b32 s11, s70, 0xfffffc00
	s_cmpk_eq_i32 s11, 0x400
	s_cselect_b32 s11, 2, 4
	s_cmpk_gt_u32 s7, 0x7fe
	s_cselect_b32 s71, s11, 0
	s_lshr_b32 s7, s5, s71
	s_lshr_b32 s5, s7, 5
	s_sext_i32_i16 s11, s5
	v_cvt_f32_i32_e32 v0, s11
	s_sext_i32_i16 s66, s6
	v_cvt_f32_i32_e32 v1, s66
	s_xor_b32 s11, s66, s11
	v_rcp_iflag_f32_e32 v2, v0
	s_ashr_i32 s11, s11, 30
	s_or_b32 s11, s11, 1
	v_and_b32_e32 v91, 31, v92
	v_mul_f32_e32 v2, v1, v2
	v_trunc_f32_e32 v2, v2
	v_fma_f32 v1, -v2, v0, v1
	v_cvt_i32_f32_e32 v2, v2
	v_cmp_ge_f32_e64 s[66:67], |v1|, |v0|
	s_and_b64 s[66:67], s[66:67], exec
	s_cselect_b32 s11, s11, 0
	v_readfirstlane_b32 s66, v2
	s_add_i32 s11, s66, s11
	s_sext_i32_i16 s66, s11
	s_mul_i32 s11, s11, s5
	s_sub_i32 s5, s6, s11
	s_sext_i32_i16 s5, s5
	s_lshl_b32 s78, s5, 5
	v_or_b32_e32 v134, s78, v91
	v_subrev_u32_e32 v87, 64, v134
	s_add_i32 s6, s7, -1
	v_max_i32_e32 v4, 0, v87
	v_min_u32_e32 v4, s6, v4
	s_add_i32 s79, s4, s66
	v_lshlrev_b32_e32 v4, s71, v4
	v_add_u32_e32 v4, s79, v4
	v_bfe_u32 v90, v92, 5, 1
	v_mad_i64_i32 v[4:5], s[4:5], v4, s62, v[84:85]
	v_lshlrev_b32_e32 v82, 4, v90
	v_lshl_add_u64 v[4:5], v[4:5], 0, s[74:75]
	v_lshl_add_u64 v[20:21], v[4:5], 0, v[82:83]
	v_max_i32_e32 v8, 0xffffffe0, v87
	v_add_co_u32_e32 v4, vcc, s63, v20
	v_add_u32_e32 v8, 32, v8
	s_nop 0
	v_addc_co_u32_e32 v5, vcc, 0, v21, vcc
	v_min_u32_e32 v8, s6, v8
	v_lshlrev_b32_e32 v86, s71, v134
	global_load_dwordx4 v[4:7], v[4:5], off
	v_lshlrev_b32_e32 v8, s71, v8
	v_add_u32_e32 v0, s79, v86
	v_add_u32_e32 v8, s79, v8
	v_mad_i64_i32 v[0:1], s[4:5], v0, s62, v[80:81]
	v_mad_i64_i32 v[8:9], s[4:5], v8, s62, v[84:85]
	v_lshl_add_u64 v[126:127], v[0:1], 0, v[82:83]
	v_lshl_add_u64 v[8:9], v[8:9], 0, s[74:75]
	global_load_dwordx4 v[0:3], v[126:127], off offset:3072
	v_lshl_add_u64 v[22:23], v[8:9], 0, v[82:83]
	v_add_co_u32_e32 v8, vcc, s63, v22
	v_max_i32_e32 v12, 0xffffffc0, v87
	s_nop 0
	v_addc_co_u32_e32 v9, vcc, 0, v23, vcc
	global_load_dwordx4 v[8:11], v[8:9], off
	v_add_u32_e32 v12, 64, v12
	v_min_u32_e32 v12, s6, v12
	s_waitcnt vmcnt(11)
	v_max_i32_e32 v16, 0xffffffa0, v87
	v_lshlrev_b32_e32 v12, s71, v12
	v_add_u32_e32 v16, 0x60, v16
	v_add_u32_e32 v12, s79, v12
	v_min_u32_e32 v16, s6, v16
	v_mad_i64_i32 v[12:13], s[4:5], v12, s62, v[84:85]
	v_lshlrev_b32_e32 v16, s71, v16
	v_lshl_add_u64 v[12:13], v[12:13], 0, s[74:75]
	v_add_u32_e32 v16, s79, v16
	v_lshl_add_u64 v[24:25], v[12:13], 0, v[82:83]
	v_mad_i64_i32 v[16:17], s[4:5], v16, s62, v[84:85]
	v_add_co_u32_e32 v12, vcc, s63, v24
	v_lshl_add_u64 v[16:17], v[16:17], 0, s[74:75]
	s_nop 0
	v_addc_co_u32_e32 v13, vcc, 0, v25, vcc
	v_lshl_add_u64 v[26:27], v[16:17], 0, v[82:83]
	v_add_co_u32_e32 v16, vcc, s63, v26
	global_load_dwordx4 v[12:15], v[12:13], off
	s_nop 0
	v_addc_co_u32_e32 v17, vcc, 0, v27, vcc
	v_lshl_add_u64 v[118:119], v[20:21], 0, s[8:9]
	v_lshl_add_u64 v[128:129], v[22:23], 0, s[8:9]
	global_load_dwordx4 v[16:19], v[16:17], off
	s_nop 0
	global_load_dwordx4 v[94:97], v[118:119], off offset:32
	global_load_dwordx4 v[98:101], v[126:127], off offset:3104
	global_load_dwordx4 v[102:105], v[118:119], off offset:96
	v_lshl_add_u64 v[130:131], v[24:25], 0, s[8:9]
	v_lshl_add_u64 v[132:133], v[26:27], 0, s[8:9]
	v_lshlrev_b32_e32 v90, 2, v90
	v_sub_u32_e32 v93, v90, v91
	s_waitcnt vmcnt(6)
	v_mfma_f32_32x32x16_bf16 v[64:79], v[4:7], v[0:3], 0
	global_load_dwordx4 v[4:7], v[128:129], off offset:32
	global_load_dwordx4 v[106:109], v[128:129], off offset:96
	global_load_dwordx4 v[110:113], v[130:131], off offset:96
	s_waitcnt vmcnt(8)
	v_mfma_f32_32x32x16_bf16 v[48:63], v[8:11], v[0:3], 0
	global_load_dwordx4 v[8:11], v[130:131], off offset:32
	s_waitcnt vmcnt(8)
	v_mfma_f32_32x32x16_bf16 v[32:47], v[12:15], v[0:3], 0
	global_load_dwordx4 v[12:15], v[132:133], off offset:32
	global_load_dwordx4 v[114:117], v[132:133], off offset:96
	s_nop 0
	global_load_dwordx4 v[118:121], v[118:119], off offset:64
	s_nop 0
	global_load_dwordx4 v[122:125], v[126:127], off offset:3136
	s_waitcnt vmcnt(9)
	v_mfma_f32_32x32x16_bf16 v[64:79], v[94:97], v[98:101], v[64:79]
	global_load_dwordx4 v[94:97], v[128:129], off offset:64
	v_mfma_f32_32x32x16_bf16 v[16:31], v[16:19], v[0:3], 0
	s_waitcnt vmcnt(4)
	v_mfma_f32_32x32x16_bf16 v[16:31], v[12:15], v[98:101], v[16:31]
	v_mfma_f32_32x32x16_bf16 v[48:63], v[4:7], v[98:101], v[48:63]
	global_load_dwordx4 v[4:7], v[130:131], off offset:64
	s_nop 0
	global_load_dwordx4 v[126:129], v[126:127], off offset:3168
	v_mfma_f32_32x32x16_bf16 v[32:47], v[8:11], v[98:101], v[32:47]
	global_load_dwordx4 v[8:11], v[132:133], off offset:64
	s_waitcnt vmcnt(3)
	v_mfma_f32_32x32x16_bf16 v[48:63], v[94:97], v[122:125], v[48:63]
	s_waitcnt vmcnt(2)
	v_mfma_f32_32x32x16_bf16 v[32:47], v[4:7], v[122:125], v[32:47]
	v_max_i32_e32 v4, 0xffffff80, v87
	v_add_u32_e32 v4, 0x80, v4
	v_min_u32_e32 v4, s6, v4
	v_lshlrev_b32_e32 v4, s71, v4
	v_add_u32_e32 v4, s79, v4
	v_mad_i64_i32 v[4:5], s[4:5], v4, s62, v[84:85]
	v_lshl_add_u64 v[4:5], v[4:5], 0, s[74:75]
	s_waitcnt vmcnt(0)
	v_mfma_f32_32x32x16_bf16 v[16:31], v[8:11], v[122:125], v[16:31]
	v_lshl_add_u64 v[8:9], v[4:5], 0, v[82:83]
	v_add_co_u32_e32 v4, vcc, s63, v8
	v_and_b32_e32 v87, 63, v92
	s_nop 0
	v_addc_co_u32_e32 v5, vcc, 0, v9, vcc
	global_load_dwordx4 v[4:7], v[4:5], off
	v_mfma_f32_32x32x16_bf16 v[64:79], v[118:121], v[122:125], v[64:79]
	v_cmp_gt_u32_e32 vcc, s64, v93
	v_mfma_f32_32x32x16_bf16 v[48:63], v[106:109], v[126:129], v[48:63]
	v_lshl_add_u64 v[106:107], v[8:9], 0, s[8:9]
	v_mfma_f32_32x32x16_bf16 v[64:79], v[102:105], v[126:129], v[64:79]
	global_load_dwordx4 v[94:97], v[106:107], off offset:32
	global_load_dwordx4 v[102:105], v[106:107], off offset:96
	s_nop 7
	v_mul_f32_e32 v48, 0x3e38aa3b, v48
	global_load_dwordx4 v[106:109], v[106:107], off offset:64
	v_mul_f32_e32 v49, 0x3e38aa3b, v49
	v_mul_f32_e32 v50, 0x3e38aa3b, v50
	v_mul_f32_e32 v51, 0x3e38aa3b, v51
	v_mul_f32_e32 v52, 0x3e38aa3b, v52
	s_waitcnt vmcnt(3)
; __device__ __forceinline__ int crow(int r, int hi) { return (r & 3) + 8 * (r >> 2) + 4 * hi; }
; __device__ __forceinline__ void dil_wave_item(const bf16* __restrict__ qkv, bf16* __restrict__ odil, float* __restrict__ lse,
;                               int pat, int g  , int head, char* wl  , const int W) {
;     ...
; #pragma unroll
;   for (int kb = 0; kb < 5; ++kb)
; #pragma unroll
;     for (int r = 0; r < 16; ++r) {
;       const int rel = kb * 32 - 64 + crow(r, hi) - r32;
;       const int kc = i0 + r32 + rel;
;       const bool ok = (rel >= -64) && (rel <= 64) && (kc >= 0) && (kc < L);
;       const float s = ok ? sc[kb][r] * AC : -1e30f;
;       sc[kb][r] = s; mx = fmaxf(mx, s);
;     ...
;     for (int i = 0; i < 4; ++i) {
;       const int key = i * 8 + (lane >> 3);
;       int kc = i0 - 64 + kb * 32 + key; kc = min(max(kc, 0), L - 1);
;       vr[i] = *reinterpret_cast<const bf16x8*>(qkv + (size_t)(tbase + kc * dil) * LDQ + 2560 + head * 64 + (lane & 7) * 8);
	v_mfma_f32_32x32x16_bf16 v[0:15], v[4:7], v[0:3], 0
	v_mul_f32_e32 v64, 0x3e38aa3b, v64
	v_mul_f32_e32 v65, 0x3e38aa3b, v65
	v_mul_f32_e32 v66, 0x3e38aa3b, v66
	v_mul_f32_e32 v67, 0x3e38aa3b, v67
	v_mul_f32_e32 v68, 0x3e38aa3b, v68
	v_mul_f32_e32 v69, 0x3e38aa3b, v69
	v_mul_f32_e32 v70, 0x3e38aa3b, v70
	s_waitcnt vmcnt(2)
	v_mfma_f32_32x32x16_bf16 v[0:15], v[94:97], v[98:101], v[0:15]
	v_add_u32_e32 v94, v134, v93
	v_subrev_u32_e32 v95, 64, v94
	v_cmp_gt_u32_e64 s[4:5], s7, v95
	s_and_b64 vcc, vcc, s[4:5]
	v_subrev_u32_e32 v95, 63, v94
	v_add_u32_e32 v96, 1, v93
	v_cndmask_b32_e32 v64, v89, v64, vcc
	v_cmp_gt_u32_e32 vcc, s64, v96
	v_cmp_gt_u32_e64 s[4:5], s7, v95
	s_waitcnt vmcnt(0)
	v_mfma_f32_32x32x16_bf16 v[0:15], v[106:109], v[122:125], v[0:15]
	v_bfe_u32 v232, v92, 3, 3
	v_and_b32_e32 v233, 7, v92
	v_add_u32_e32 v232, s78, v232
	v_lshlrev_b32_e32 v233, 4, v233
	v_add_u32_e32 v233, s74, v233
	v_add_u32_e32 v233, 0x1400, v233
	v_add_u32_e32 v234, 0xffffffc0, v232
	v_max_i32_e32 v234, 0, v234
	v_min_u32_e32 v234, s6, v234
	v_lshlrev_b32_e32 v234, s71, v234
	v_add_u32_e32 v234, s79, v234
	v_mad_u32_u24 v234, v234, s62, v233
	global_load_dwordx4 v[152:155], v234, s[36:37]
	v_add_u32_e32 v235, 0xffffffc8, v232
	v_max_i32_e32 v235, 0, v235
	v_min_u32_e32 v235, s6, v235
	v_lshlrev_b32_e32 v235, s71, v235
	v_add_u32_e32 v235, s79, v235
	v_mad_u32_u24 v235, v235, s62, v233
	global_load_dwordx4 v[156:159], v235, s[36:37]
	v_add_u32_e32 v234, 0xffffffd0, v232
	v_max_i32_e32 v234, 0, v234
	v_min_u32_e32 v234, s6, v234
	v_lshlrev_b32_e32 v234, s71, v234
	v_add_u32_e32 v234, s79, v234
	v_mad_u32_u24 v234, v234, s62, v233
	global_load_dwordx4 v[160:163], v234, s[36:37]
	v_add_u32_e32 v235, 0xffffffd8, v232
	v_max_i32_e32 v235, 0, v235
	v_min_u32_e32 v235, s6, v235
	v_lshlrev_b32_e32 v235, s71, v235
	v_add_u32_e32 v235, s79, v235
	v_mad_u32_u24 v235, v235, s62, v233
	global_load_dwordx4 v[164:167], v235, s[36:37]
	v_add_u32_e32 v234, 0xffffffe0, v232
	v_max_i32_e32 v234, 0, v234
	v_min_u32_e32 v234, s6, v234
	v_lshlrev_b32_e32 v234, s71, v234
	v_add_u32_e32 v234, s79, v234
	v_mad_u32_u24 v234, v234, s62, v233
	global_load_dwordx4 v[168:171], v234, s[36:37]
	v_add_u32_e32 v235, 0xffffffe8, v232
	v_max_i32_e32 v235, 0, v235
	v_min_u32_e32 v235, s6, v235
	v_lshlrev_b32_e32 v235, s71, v235
	v_add_u32_e32 v235, s79, v235
	v_mad_u32_u24 v235, v235, s62, v233
	global_load_dwordx4 v[172:175], v235, s[36:37]
	v_add_u32_e32 v234, -16, v232
	v_max_i32_e32 v234, 0, v234
	v_min_u32_e32 v234, s6, v234
	v_lshlrev_b32_e32 v234, s71, v234
	v_add_u32_e32 v234, s79, v234
	v_mad_u32_u24 v234, v234, s62, v233
	global_load_dwordx4 v[176:179], v234, s[36:37]
	v_add_u32_e32 v235, -8, v232
	v_max_i32_e32 v235, 0, v235
	v_min_u32_e32 v235, s6, v235
	v_lshlrev_b32_e32 v235, s71, v235
	v_add_u32_e32 v235, s79, v235
	v_mad_u32_u24 v235, v235, s62, v233
	global_load_dwordx4 v[180:183], v235, s[36:37]
	v_add_u32_e32 v234, 0, v232
	v_max_i32_e32 v234, 0, v234
	v_min_u32_e32 v234, s6, v234
	v_lshlrev_b32_e32 v234, s71, v234
	v_add_u32_e32 v234, s79, v234
	v_mad_u32_u24 v234, v234, s62, v233
	global_load_dwordx4 v[184:187], v234, s[36:37]
	v_add_u32_e32 v235, 8, v232
	v_max_i32_e32 v235, 0, v235
	v_min_u32_e32 v235, s6, v235
	v_lshlrev_b32_e32 v235, s71, v235
	v_add_u32_e32 v235, s79, v235
	v_mad_u32_u24 v235, v235, s62, v233
	global_load_dwordx4 v[188:191], v235, s[36:37]
	v_add_u32_e32 v234, 16, v232
	v_max_i32_e32 v234, 0, v234
	v_min_u32_e32 v234, s6, v234
	v_lshlrev_b32_e32 v234, s71, v234
	v_add_u32_e32 v234, s79, v234
	v_mad_u32_u24 v234, v234, s62, v233
	global_load_dwordx4 v[192:195], v234, s[36:37]
	v_add_u32_e32 v235, 24, v232
	v_max_i32_e32 v235, 0, v235
	v_min_u32_e32 v235, s6, v235
	v_lshlrev_b32_e32 v235, s71, v235
	v_add_u32_e32 v235, s79, v235
	v_mad_u32_u24 v235, v235, s62, v233
	global_load_dwordx4 v[196:199], v235, s[36:37]
	v_add_u32_e32 v234, 32, v232
	v_max_i32_e32 v234, 0, v234
	v_min_u32_e32 v234, s6, v234
	v_lshlrev_b32_e32 v234, s71, v234
	v_add_u32_e32 v234, s79, v234
	v_mad_u32_u24 v234, v234, s62, v233
	global_load_dwordx4 v[200:203], v234, s[36:37]
	v_add_u32_e32 v235, 40, v232
	v_max_i32_e32 v235, 0, v235
	v_min_u32_e32 v235, s6, v235
	v_lshlrev_b32_e32 v235, s71, v235
	v_add_u32_e32 v235, s79, v235
	v_mad_u32_u24 v235, v235, s62, v233
	global_load_dwordx4 v[204:207], v235, s[36:37]
	v_add_u32_e32 v234, 48, v232
	v_max_i32_e32 v234, 0, v234
	v_min_u32_e32 v234, s6, v234
	v_lshlrev_b32_e32 v234, s71, v234
	v_add_u32_e32 v234, s79, v234
	v_mad_u32_u24 v234, v234, s62, v233
	global_load_dwordx4 v[208:211], v234, s[36:37]
	v_add_u32_e32 v235, 56, v232
	v_max_i32_e32 v235, 0, v235
	v_min_u32_e32 v235, s6, v235
	v_lshlrev_b32_e32 v235, s71, v235
	v_add_u32_e32 v235, s79, v235
	v_mad_u32_u24 v235, v235, s62, v233
	global_load_dwordx4 v[212:215], v235, s[36:37]
	v_add_u32_e32 v234, 64, v232
	v_max_i32_e32 v234, 0, v234
	v_min_u32_e32 v234, s6, v234
	v_lshlrev_b32_e32 v234, s71, v234
	v_add_u32_e32 v234, s79, v234
	v_mad_u32_u24 v234, v234, s62, v233
	global_load_dwordx4 v[216:219], v234, s[36:37]
	v_add_u32_e32 v235, 0x00000048, v232
	v_max_i32_e32 v235, 0, v235
	v_min_u32_e32 v235, s6, v235
	v_lshlrev_b32_e32 v235, s71, v235
	v_add_u32_e32 v235, s79, v235
	v_mad_u32_u24 v235, v235, s62, v233
	global_load_dwordx4 v[220:223], v235, s[36:37]
	v_add_u32_e32 v234, 0x00000050, v232
	v_max_i32_e32 v234, 0, v234
	v_min_u32_e32 v234, s6, v234
	v_lshlrev_b32_e32 v234, s71, v234
	v_add_u32_e32 v234, s79, v234
	v_mad_u32_u24 v234, v234, s62, v233
	global_load_dwordx4 v[224:227], v234, s[36:37]
	v_add_u32_e32 v235, 0x00000058, v232
	v_max_i32_e32 v235, 0, v235
; __device__ __forceinline__ int crow(int r, int hi) { return (r & 3) + 8 * (r >> 2) + 4 * hi; }
; __device__ __forceinline__ void dil_wave_item(const bf16* __restrict__ qkv, bf16* __restrict__ odil, float* __restrict__ lse,
;                               int pat, int g  , int head, char* wl  , const int W) {
;     ...
; #pragma unroll
;   for (int kb = 0; kb < 5; ++kb)
; #pragma unroll
;     for (int r = 0; r < 16; ++r) {
;       const int rel = kb * 32 - 64 + crow(r, hi) - r32;
;       const int kc = i0 + r32 + rel;
;       const bool ok = (rel >= -64) && (rel <= 64) && (kc >= 0) && (kc < L);
;       const float s = ok ? sc[kb][r] * AC : -1e30f;
;       sc[kb][r] = s; mx = fmaxf(mx, s);
;     }
	v_min_u32_e32 v235, s6, v235
	v_lshlrev_b32_e32 v235, s71, v235
	v_add_u32_e32 v235, s79, v235
	v_mad_u32_u24 v235, v235, s62, v233
	global_load_dwordx4 v[228:231], v235, s[36:37]
	s_and_b64 vcc, vcc, s[4:5]
	v_subrev_u32_e32 v97, 62, v94
	v_add_u32_e32 v98, 2, v93
	v_cndmask_b32_e32 v65, v89, v65, vcc
	v_cmp_gt_u32_e32 vcc, s64, v98
	v_cmp_gt_u32_e64 s[4:5], s7, v97
	s_and_b64 vcc, vcc, s[4:5]
	v_subrev_u32_e32 v97, 61, v94
	v_add_u32_e32 v99, 3, v93
	v_cndmask_b32_e32 v66, v89, v66, vcc
	v_cmp_gt_u32_e32 vcc, s64, v99
	v_cmp_gt_u32_e64 s[4:5], s7, v97
	s_and_b64 vcc, vcc, s[4:5]
	v_subrev_u32_e32 v97, 56, v94
	v_add_u32_e32 v100, 8, v93
	v_cndmask_b32_e32 v67, v89, v67, vcc
	v_cmp_gt_u32_e32 vcc, s64, v100
	v_cmp_gt_u32_e64 s[4:5], s7, v97
	s_and_b64 vcc, vcc, s[4:5]
	v_subrev_u32_e32 v97, 55, v94
	v_add_u32_e32 v101, 9, v93
	v_cndmask_b32_e32 v68, v89, v68, vcc
	v_cmp_gt_u32_e32 vcc, s64, v101
	v_cmp_gt_u32_e64 s[4:5], s7, v97
	v_mfma_f32_32x32x16_bf16 v[0:15], v[102:105], v[126:129], v[0:15]
	s_and_b64 vcc, vcc, s[4:5]
	v_subrev_u32_e32 v97, 54, v94
	v_add_u32_e32 v102, 10, v93
	v_cndmask_b32_e32 v69, v89, v69, vcc
	v_cmp_gt_u32_e32 vcc, s64, v102
	v_cmp_gt_u32_e64 s[4:5], s7, v97
	s_and_b64 vcc, vcc, s[4:5]
	v_subrev_u32_e32 v97, 53, v94
	v_add_u32_e32 v103, 11, v93
	v_cndmask_b32_e32 v70, v89, v70, vcc
	v_cmp_gt_u32_e32 vcc, s64, v103
	v_cmp_gt_u32_e64 s[4:5], s7, v97
	v_mul_f32_e32 v71, 0x3e38aa3b, v71
	s_and_b64 vcc, vcc, s[4:5]
	v_subrev_u32_e32 v97, 48, v94
	v_add_u32_e32 v104, 16, v93
	v_cndmask_b32_e32 v71, v89, v71, vcc
	v_cmp_gt_u32_e32 vcc, s64, v104
	v_cmp_gt_u32_e64 s[4:5], s7, v97
	v_mul_f32_e32 v72, 0x3e38aa3b, v72
	s_and_b64 vcc, vcc, s[4:5]
	v_subrev_u32_e32 v97, 47, v94
	v_add_u32_e32 v105, 17, v93
	v_cndmask_b32_e32 v72, v89, v72, vcc
	v_cmp_gt_u32_e32 vcc, s64, v105
	v_cmp_gt_u32_e64 s[4:5], s7, v97
	v_mul_f32_e32 v73, 0x3e38aa3b, v73
	s_and_b64 vcc, vcc, s[4:5]
	v_subrev_u32_e32 v97, 46, v94
	v_add_u32_e32 v106, 18, v93
	v_cndmask_b32_e32 v73, v89, v73, vcc
	v_cmp_gt_u32_e32 vcc, s64, v106
	v_cmp_gt_u32_e64 s[4:5], s7, v97
	v_mul_f32_e32 v74, 0x3e38aa3b, v74
	s_and_b64 vcc, vcc, s[4:5]
	v_subrev_u32_e32 v97, 45, v94
	v_add_u32_e32 v107, 19, v93
	v_cndmask_b32_e32 v74, v89, v74, vcc
	v_cmp_gt_u32_e32 vcc, s64, v107
	v_cmp_gt_u32_e64 s[4:5], s7, v97
	v_mul_f32_e32 v75, 0x3e38aa3b, v75
	s_and_b64 vcc, vcc, s[4:5]
	v_subrev_u32_e32 v97, 40, v94
	v_add_u32_e32 v108, 24, v93
	v_cndmask_b32_e32 v75, v89, v75, vcc
	v_cmp_gt_u32_e32 vcc, s64, v108
	v_cmp_gt_u32_e64 s[4:5], s7, v97
	v_mul_f32_e32 v76, 0x3e38aa3b, v76
	s_and_b64 vcc, vcc, s[4:5]
	v_subrev_u32_e32 v97, 39, v94
	v_add_u32_e32 v109, 25, v93
	v_cndmask_b32_e32 v76, v89, v76, vcc
	v_cmp_gt_u32_e32 vcc, s64, v109
	v_cmp_gt_u32_e64 s[4:5], s7, v97
	v_mfma_f32_32x32x16_bf16 v[32:47], v[110:113], v[126:129], v[32:47]
	v_mul_f32_e32 v77, 0x3e38aa3b, v77
	s_and_b64 vcc, vcc, s[4:5]
	v_subrev_u32_e32 v97, 38, v94
	v_add_u32_e32 v110, 26, v93
	v_cndmask_b32_e32 v77, v89, v77, vcc
	v_cmp_gt_u32_e32 vcc, s64, v110
	v_cmp_gt_u32_e64 s[4:5], s7, v97
	v_mul_f32_e32 v78, 0x3e38aa3b, v78
	s_and_b64 vcc, vcc, s[4:5]
	v_subrev_u32_e32 v97, 37, v94
	v_add_u32_e32 v111, 27, v93
	v_cndmask_b32_e32 v78, v89, v78, vcc
	v_cmp_gt_u32_e32 vcc, s64, v111
	v_cmp_gt_u32_e64 s[4:5], s7, v97
	v_mul_f32_e32 v79, 0x3e38aa3b, v79
	s_and_b64 vcc, vcc, s[4:5]
	v_subrev_u32_e32 v97, 32, v94
	v_cndmask_b32_e32 v79, v89, v79, vcc
	v_cmp_gt_u32_e32 vcc, s7, v97
	v_subrev_u32_e32 v97, 31, v94
	v_max3_f32 v95, v64, s65, v65
	v_cndmask_b32_e32 v48, v89, v48, vcc
	v_cmp_gt_u32_e32 vcc, s7, v97
	v_subrev_u32_e32 v97, 30, v94
	v_mul_f32_e32 v53, 0x3e38aa3b, v53
	v_cndmask_b32_e32 v49, v89, v49, vcc
	v_cmp_gt_u32_e32 vcc, s7, v97
	v_subrev_u32_e32 v97, 29, v94
	v_max3_f32 v95, v95, v66, v67
	v_cndmask_b32_e32 v50, v89, v50, vcc
	v_cmp_gt_u32_e32 vcc, s7, v97
	v_subrev_u32_e32 v97, 24, v94
	v_mul_f32_e32 v54, 0x3e38aa3b, v54
	v_cndmask_b32_e32 v51, v89, v51, vcc
	v_cmp_gt_u32_e32 vcc, s7, v97
	v_subrev_u32_e32 v97, 23, v94
	v_max3_f32 v95, v95, v68, v69
	v_cndmask_b32_e32 v52, v89, v52, vcc
	v_cmp_gt_u32_e32 vcc, s7, v97
	v_subrev_u32_e32 v97, 22, v94
	v_mul_f32_e32 v55, 0x3e38aa3b, v55
	v_cndmask_b32_e32 v53, v89, v53, vcc
	v_cmp_gt_u32_e32 vcc, s7, v97
	v_subrev_u32_e32 v97, 21, v94
	v_max3_f32 v95, v95, v70, v71
	v_cndmask_b32_e32 v54, v89, v54, vcc
	v_cmp_gt_u32_e32 vcc, s7, v97
	v_add_u32_e32 v97, -16, v94
	v_mul_f32_e32 v56, 0x3e38aa3b, v56
	v_cndmask_b32_e32 v55, v89, v55, vcc
	v_cmp_gt_u32_e32 vcc, s7, v97
	v_add_u32_e32 v97, -15, v94
	v_max3_f32 v95, v95, v72, v73
	v_cndmask_b32_e32 v56, v89, v56, vcc
	v_mul_f32_e32 v57, 0x3e38aa3b, v57
	v_cmp_gt_u32_e32 vcc, s7, v97
	v_add_u32_e32 v97, -14, v94
	v_max3_f32 v95, v95, v74, v75
	v_cndmask_b32_e32 v57, v89, v57, vcc
	v_mul_f32_e32 v58, 0x3e38aa3b, v58
	v_cmp_gt_u32_e32 vcc, s7, v97
	v_add_u32_e32 v97, -13, v94
	v_max3_f32 v95, v95, v76, v77
	v_cndmask_b32_e32 v58, v89, v58, vcc
	v_mul_f32_e32 v59, 0x3e38aa3b, v59
	v_cmp_gt_u32_e32 vcc, s7, v97
	v_add_u32_e32 v97, -8, v94
	v_max3_f32 v95, v95, v78, v79
	v_cndmask_b32_e32 v59, v89, v59, vcc
	v_mul_f32_e32 v60, 0x3e38aa3b, v60
	v_cmp_gt_u32_e32 vcc, s7, v97
	v_add_u32_e32 v97, -7, v94
	v_max3_f32 v95, v95, v48, v49
	v_cndmask_b32_e32 v60, v89, v60, vcc
	v_mul_f32_e32 v61, 0x3e38aa3b, v61
	v_cmp_gt_u32_e32 vcc, s7, v97
	v_add_u32_e32 v97, -6, v94
	v_max3_f32 v95, v95, v50, v51
	v_cndmask_b32_e32 v61, v89, v61, vcc
	v_mul_f32_e32 v62, 0x3e38aa3b, v62
	v_cmp_gt_u32_e32 vcc, s7, v97
	v_add_u32_e32 v97, -5, v94
	v_max3_f32 v95, v95, v52, v53
	v_cndmask_b32_e32 v62, v89, v62, vcc
	v_mul_f32_e32 v63, 0x3e38aa3b, v63
; __device__ __forceinline__ int crow(int r, int hi) { return (r & 3) + 8 * (r >> 2) + 4 * hi; }
; __device__ __forceinline__ void dil_wave_item(const bf16* __restrict__ qkv, bf16* __restrict__ odil, float* __restrict__ lse,
;                               int pat, int g  , int head, char* wl  , const int W) {
;     ...
; #pragma unroll
;   for (int kb = 0; kb < 5; ++kb)
; #pragma unroll
;     for (int r = 0; r < 16; ++r) {
;       const int rel = kb * 32 - 64 + crow(r, hi) - r32;
;       const int kc = i0 + r32 + rel;
;       const bool ok = (rel >= -64) && (rel <= 64) && (kc >= 0) && (kc < L);
;       const float s = ok ? sc[kb][r] * AC : -1e30f;
;       sc[kb][r] = s; mx = fmaxf(mx, s);
;     }
	v_cmp_gt_u32_e32 vcc, s7, v97
	v_max3_f32 v95, v95, v54, v55
	v_mul_f32_e32 v32, 0x3e38aa3b, v32
	v_cndmask_b32_e32 v63, v89, v63, vcc
	v_cmp_gt_u32_e32 vcc, s7, v94
	v_add_u32_e32 v96, v134, v96
	v_max3_f32 v95, v95, v56, v57
	v_cndmask_b32_e32 v32, v89, v32, vcc
	v_mul_f32_e32 v33, 0x3e38aa3b, v33
	v_cmp_gt_u32_e32 vcc, s7, v96
	v_add_u32_e32 v96, v134, v98
	v_max3_f32 v95, v95, v58, v59
	v_cndmask_b32_e32 v33, v89, v33, vcc
	v_mul_f32_e32 v34, 0x3e38aa3b, v34
	v_cmp_gt_u32_e32 vcc, s7, v96
	v_max3_f32 v95, v95, v60, v61
	v_max3_f32 v95, v95, v62, v63
	v_cndmask_b32_e32 v96, v89, v34, vcc
	v_add_u32_e32 v34, v134, v99
	v_mul_f32_e32 v35, 0x3e38aa3b, v35
	v_cmp_gt_u32_e32 vcc, s7, v34
	v_max3_f32 v95, v95, v32, v33
	v_mul_f32_e32 v36, 0x3e38aa3b, v36
	v_cndmask_b32_e32 v35, v89, v35, vcc
	v_max3_f32 v34, v95, v96, v35
	v_add_u32_e32 v95, v134, v100
	v_cmp_gt_u32_e32 vcc, s7, v95
	v_add_u32_e32 v95, v134, v101
	v_mul_f32_e32 v37, 0x3e38aa3b, v37
	v_cndmask_b32_e32 v36, v89, v36, vcc
	v_cmp_gt_u32_e32 vcc, s7, v95
	v_add_u32_e32 v95, v134, v102
	v_mul_f32_e32 v38, 0x3e38aa3b, v38
	v_cndmask_b32_e32 v37, v89, v37, vcc
	v_cmp_gt_u32_e32 vcc, s7, v95
	v_add_u32_e32 v95, v134, v103
	v_mul_f32_e32 v39, 0x3e38aa3b, v39
	v_cndmask_b32_e32 v38, v89, v38, vcc
	v_cmp_gt_u32_e32 vcc, s7, v95
	v_add_u32_e32 v95, v134, v104
	v_mfma_f32_32x32x16_bf16 v[16:31], v[114:117], v[126:129], v[16:31]
	v_cndmask_b32_e32 v39, v89, v39, vcc
	v_mul_f32_e32 v40, 0x3e38aa3b, v40
	v_cmp_gt_u32_e32 vcc, s7, v95
	v_add_u32_e32 v95, v134, v105
	v_mul_f32_e32 v41, 0x3e38aa3b, v41
	v_cndmask_b32_e32 v40, v89, v40, vcc
	v_cmp_gt_u32_e32 vcc, s7, v95
	v_add_u32_e32 v95, v134, v106
	v_mul_f32_e32 v42, 0x3e38aa3b, v42
	v_cndmask_b32_e32 v41, v89, v41, vcc
	v_cmp_gt_u32_e32 vcc, s7, v95
	v_add_u32_e32 v95, v134, v107
	v_mul_f32_e32 v43, 0x3e38aa3b, v43
	v_cndmask_b32_e32 v42, v89, v42, vcc
	v_cmp_gt_u32_e32 vcc, s7, v95
	v_add_u32_e32 v95, v134, v108
	v_mul_f32_e32 v44, 0x3e38aa3b, v44
	v_cndmask_b32_e32 v43, v89, v43, vcc
	v_cmp_gt_u32_e32 vcc, s7, v95
	v_add_u32_e32 v95, v134, v109
	v_mul_f32_e32 v45, 0x3e38aa3b, v45
	v_cndmask_b32_e32 v44, v89, v44, vcc
	v_cmp_gt_u32_e32 vcc, s7, v95
	v_add_u32_e32 v95, v134, v110
	v_mul_f32_e32 v46, 0x3e38aa3b, v46
	v_cndmask_b32_e32 v45, v89, v45, vcc
	v_cmp_gt_u32_e32 vcc, s7, v95
	v_add_u32_e32 v95, v134, v111
	v_mul_f32_e32 v47, 0x3e38aa3b, v47
	v_cndmask_b32_e32 v46, v89, v46, vcc
	v_cmp_gt_u32_e32 vcc, s7, v95
	v_add_u32_e32 v95, 32, v94
	v_mul_f32_e32 v16, 0x3e38aa3b, v16
	v_cndmask_b32_e32 v47, v89, v47, vcc
	v_cmp_gt_u32_e32 vcc, s7, v95
	v_add_u32_e32 v95, 33, v94
	v_mul_f32_e32 v17, 0x3e38aa3b, v17
	v_cndmask_b32_e32 v16, v89, v16, vcc
	v_cmp_gt_u32_e32 vcc, s7, v95
	v_add_u32_e32 v95, 34, v94
	v_mul_f32_e32 v18, 0x3e38aa3b, v18
	v_cndmask_b32_e32 v17, v89, v17, vcc
	v_cmp_gt_u32_e32 vcc, s7, v95
	v_add_u32_e32 v95, 35, v94
	v_mul_f32_e32 v19, 0x3e38aa3b, v19
	v_cndmask_b32_e32 v18, v89, v18, vcc
	v_cmp_gt_u32_e32 vcc, s7, v95
	v_add_u32_e32 v95, 40, v94
	v_mul_f32_e32 v20, 0x3e38aa3b, v20
	v_cndmask_b32_e32 v19, v89, v19, vcc
	v_cmp_gt_u32_e32 vcc, s7, v95
	v_add_u32_e32 v95, 41, v94
	v_mul_f32_e32 v21, 0x3e38aa3b, v21
	v_cndmask_b32_e32 v20, v89, v20, vcc
	v_cmp_gt_u32_e32 vcc, s7, v95
	v_add_u32_e32 v95, 42, v94
	v_mul_f32_e32 v22, 0x3e38aa3b, v22
	v_cndmask_b32_e32 v21, v89, v21, vcc
	v_cmp_gt_u32_e32 vcc, s7, v95
	v_add_u32_e32 v95, 43, v94
	v_mul_f32_e32 v23, 0x3e38aa3b, v23
	v_cndmask_b32_e32 v22, v89, v22, vcc
	v_cmp_gt_u32_e32 vcc, s7, v95
	v_add_u32_e32 v95, 48, v94
	v_max3_f32 v34, v34, v36, v37
	v_cndmask_b32_e32 v23, v89, v23, vcc
	v_mul_f32_e32 v24, 0x3e38aa3b, v24
	v_cmp_gt_u32_e32 vcc, s7, v95
	v_add_u32_e32 v95, 49, v94
	v_max3_f32 v34, v34, v38, v39
	v_cndmask_b32_e32 v24, v89, v24, vcc
	v_mul_f32_e32 v25, 0x3e38aa3b, v25
	v_cmp_gt_u32_e32 vcc, s7, v95
	v_add_u32_e32 v95, 50, v94
	v_max3_f32 v34, v34, v40, v41
	v_cndmask_b32_e32 v25, v89, v25, vcc
	v_mul_f32_e32 v26, 0x3e38aa3b, v26
	v_cmp_gt_u32_e32 vcc, s7, v95
	v_add_u32_e32 v95, 51, v94
	v_max3_f32 v34, v34, v42, v43
	v_cndmask_b32_e32 v26, v89, v26, vcc
	v_mul_f32_e32 v27, 0x3e38aa3b, v27
	v_cmp_gt_u32_e32 vcc, s7, v95
	v_add_u32_e32 v95, 56, v94
	v_max3_f32 v34, v34, v44, v45
	v_cndmask_b32_e32 v27, v89, v27, vcc
	v_mul_f32_e32 v28, 0x3e38aa3b, v28
	v_cmp_gt_u32_e32 vcc, s7, v95
	v_add_u32_e32 v95, 57, v94
	v_max3_f32 v34, v34, v46, v47
	v_cndmask_b32_e32 v28, v89, v28, vcc
	v_mul_f32_e32 v29, 0x3e38aa3b, v29
	v_cmp_gt_u32_e32 vcc, s7, v95
	v_add_u32_e32 v95, 58, v94
	v_max3_f32 v34, v34, v16, v17
	v_cndmask_b32_e32 v29, v89, v29, vcc
	v_mul_f32_e32 v30, 0x3e38aa3b, v30
	v_cmp_gt_u32_e32 vcc, s7, v95
	v_add_u32_e32 v95, 59, v94
	v_max3_f32 v34, v34, v18, v19
	v_cndmask_b32_e32 v30, v89, v30, vcc
	v_mul_f32_e32 v31, 0x3e38aa3b, v31
	v_cmp_gt_u32_e32 vcc, s7, v95
	v_add_u32_e32 v95, 64, v94
	v_add_u32_e32 v97, 0x80, v93
	v_max3_f32 v34, v34, v20, v21
	v_cndmask_b32_e32 v31, v89, v31, vcc
	v_cmp_gt_u32_e32 vcc, s64, v97
	v_cmp_gt_u32_e64 s[4:5], s7, v95
	v_max3_f32 v34, v34, v22, v23
	v_mul_f32_e32 v0, 0x3e38aa3b, v0
	s_and_b64 vcc, vcc, s[4:5]
	v_max3_f32 v34, v34, v24, v25
	v_cndmask_b32_e32 v98, v89, v0, vcc
	v_add_u32_e32 v0, 0x41, v94
	v_max3_f32 v34, v34, v26, v27
	v_cmp_lt_u32_e32 vcc, s68, v93
	v_cmp_gt_u32_e64 s[4:5], s7, v0
	v_max3_f32 v34, v34, v28, v29
	v_mul_f32_e32 v0, 0x3e38aa3b, v1
	s_and_b64 vcc, vcc, s[4:5]
	v_max3_f32 v34, v34, v30, v31
	v_cndmask_b32_e32 v99, v89, v0, vcc
	v_max3_f32 v0, v34, v98, v99
	v_add_u32_e32 v1, 0x42, v94
	v_add_u32_e32 v34, 0x82, v93
	v_cmp_gt_u32_e32 vcc, s64, v34
	v_cmp_gt_u32_e64 s[4:5], s7, v1
; __device__ __forceinline__ float shfl_idx(float v, int srclane) { return __int_as_float(__builtin_amdgcn_ds_bpermute(srclane << 2, __float_as_int(v))); }
; __device__ __forceinline__ void dil_wave_item(const bf16* __restrict__ qkv, bf16* __restrict__ odil, float* __restrict__ lse,
;                               int pat, int g  , int head, char* wl  , const int W) {
;     ...
;     }
;   mx = fmaxf(mx, shfl_idx(mx, lane ^ 32));
;   float ls = 0.f;
; #pragma unroll
;   for (int kb = 0; kb < 5; ++kb)
; #pragma unroll
;     for (int r = 0; r < 16; ++r) { const float e = __builtin_amdgcn_exp2f(sc[kb][r] - mx); sc[kb][r] = e; ls += e; }
;   ls += shfl_idx(ls, lane ^ 32);
	v_mul_f32_e32 v1, 0x3e38aa3b, v2
	s_and_b64 vcc, vcc, s[4:5]
	v_cndmask_b32_e32 v100, v89, v1, vcc
	v_add_u32_e32 v1, 0x43, v94
	v_add_u32_e32 v2, 0x83, v93
	v_cmp_gt_u32_e32 vcc, s64, v2
	v_cmp_gt_u32_e64 s[4:5], s7, v1
	v_mul_f32_e32 v1, 0x3e38aa3b, v3
	s_and_b64 vcc, vcc, s[4:5]
	v_cndmask_b32_e32 v101, v89, v1, vcc
	v_add_u32_e32 v1, 0x48, v94
	v_add_u32_e32 v2, 0x88, v93
	v_cmp_gt_u32_e32 vcc, s64, v2
	v_cmp_gt_u32_e64 s[4:5], s7, v1
	v_mul_f32_e32 v1, 0x3e38aa3b, v4
	s_and_b64 vcc, vcc, s[4:5]
	v_cndmask_b32_e32 v102, v89, v1, vcc
	v_add_u32_e32 v1, 0x49, v94
	v_add_u32_e32 v2, 0x89, v93
	v_cmp_gt_u32_e32 vcc, s64, v2
	v_cmp_gt_u32_e64 s[4:5], s7, v1
	v_mul_f32_e32 v1, 0x3e38aa3b, v5
	s_and_b64 vcc, vcc, s[4:5]
	v_cndmask_b32_e32 v103, v89, v1, vcc
	v_add_u32_e32 v1, 0x4a, v94
	v_add_u32_e32 v2, 0x8a, v93
	v_cmp_gt_u32_e32 vcc, s64, v2
	v_cmp_gt_u32_e64 s[4:5], s7, v1
	v_mul_f32_e32 v1, 0x3e38aa3b, v6
	s_and_b64 vcc, vcc, s[4:5]
	v_cndmask_b32_e32 v104, v89, v1, vcc
	v_add_u32_e32 v1, 0x4b, v94
	v_add_u32_e32 v2, 0x8b, v93
	v_cmp_gt_u32_e32 vcc, s64, v2
	v_cmp_gt_u32_e64 s[4:5], s7, v1
	v_mul_f32_e32 v1, 0x3e38aa3b, v7
	s_and_b64 vcc, vcc, s[4:5]
	v_cndmask_b32_e32 v105, v89, v1, vcc
	v_add_u32_e32 v1, 0x50, v94
	v_add_u32_e32 v2, 0x90, v93
	v_cmp_gt_u32_e32 vcc, s64, v2
	v_cmp_gt_u32_e64 s[4:5], s7, v1
	v_mul_f32_e32 v1, 0x3e38aa3b, v8
	s_and_b64 vcc, vcc, s[4:5]
	v_cndmask_b32_e32 v106, v89, v1, vcc
	v_add_u32_e32 v1, 0x51, v94
	v_add_u32_e32 v2, 0x91, v93
	v_cmp_gt_u32_e32 vcc, s64, v2
	v_cmp_gt_u32_e64 s[4:5], s7, v1
	v_mul_f32_e32 v1, 0x3e38aa3b, v9
	s_and_b64 vcc, vcc, s[4:5]
	v_cndmask_b32_e32 v107, v89, v1, vcc
	v_add_u32_e32 v1, 0x52, v94
	v_add_u32_e32 v2, 0x92, v93
	v_cmp_gt_u32_e32 vcc, s64, v2
	v_cmp_gt_u32_e64 s[4:5], s7, v1
	v_mul_f32_e32 v1, 0x3e38aa3b, v10
	s_and_b64 vcc, vcc, s[4:5]
	v_cndmask_b32_e32 v108, v89, v1, vcc
	v_add_u32_e32 v1, 0x53, v94
	v_add_u32_e32 v2, 0x93, v93
	v_cmp_gt_u32_e32 vcc, s64, v2
	v_cmp_gt_u32_e64 s[4:5], s7, v1
	v_mul_f32_e32 v1, 0x3e38aa3b, v11
	s_and_b64 vcc, vcc, s[4:5]
	v_cndmask_b32_e32 v109, v89, v1, vcc
	v_add_u32_e32 v1, 0x58, v94
	v_add_u32_e32 v2, 0x98, v93
	v_cmp_gt_u32_e32 vcc, s64, v2
	v_cmp_gt_u32_e64 s[4:5], s7, v1
	v_mul_f32_e32 v1, 0x3e38aa3b, v12
	s_and_b64 vcc, vcc, s[4:5]
	v_cndmask_b32_e32 v110, v89, v1, vcc
	v_add_u32_e32 v1, 0x59, v94
	v_add_u32_e32 v2, 0x99, v93
	v_cmp_gt_u32_e32 vcc, s64, v2
	v_cmp_gt_u32_e64 s[4:5], s7, v1
	v_mul_f32_e32 v1, 0x3e38aa3b, v13
	s_and_b64 vcc, vcc, s[4:5]
	v_cndmask_b32_e32 v111, v89, v1, vcc
	v_add_u32_e32 v1, 0x5a, v94
	v_add_u32_e32 v2, 0x9a, v93
	v_max3_f32 v0, v0, v100, v101
	v_cmp_gt_u32_e32 vcc, s64, v2
	v_cmp_gt_u32_e64 s[4:5], s7, v1
	v_max3_f32 v0, v0, v102, v103
	v_mul_f32_e32 v1, 0x3e38aa3b, v14
	s_and_b64 vcc, vcc, s[4:5]
	v_max3_f32 v0, v0, v104, v105
	v_cndmask_b32_e32 v112, v89, v1, vcc
	v_add_u32_e32 v1, 0x5b, v94
	v_add_u32_e32 v2, 0x9b, v93
	v_max3_f32 v0, v0, v106, v107
	v_cmp_gt_u32_e32 vcc, s64, v2
	v_cmp_gt_u32_e64 s[4:5], s7, v1
	v_max3_f32 v0, v0, v108, v109
	v_mul_f32_e32 v1, 0x3e38aa3b, v15
	s_and_b64 vcc, vcc, s[4:5]
	v_max3_f32 v0, v0, v110, v111
	v_cndmask_b32_e32 v113, v89, v1, vcc
	v_lshlrev_b32_e32 v1, 2, v87
	v_max3_f32 v0, v0, v112, v113
	v_xor_b32_e32 v114, 0x80, v1
	ds_bpermute_b32 v1, v114, v0
	s_waitcnt lgkmcnt(0)
	v_max_f32_e32 v1, v1, v1
	v_max_f32_e32 v34, v0, v1
	v_sub_f32_e32 v0, v64, v34
	v_exp_f32_e32 v115, v0
	v_sub_f32_e32 v0, v65, v34
	v_exp_f32_e32 v116, v0
	v_sub_f32_e32 v0, v66, v34
	v_exp_f32_e32 v117, v0
	v_sub_f32_e32 v0, v67, v34
	v_exp_f32_e32 v118, v0
	v_sub_f32_e32 v1, v68, v34
	v_add_f32_e32 v0, 0, v115
	v_exp_f32_e32 v119, v1
	v_sub_f32_e32 v1, v69, v34
	v_add_f32_e32 v0, v116, v0
	v_exp_f32_e32 v120, v1
	v_sub_f32_e32 v1, v70, v34
	v_add_f32_e32 v0, v117, v0
	v_exp_f32_e32 v121, v1
	v_sub_f32_e32 v1, v71, v34
	v_add_f32_e32 v0, v118, v0
	v_exp_f32_e32 v122, v1
	v_sub_f32_e32 v1, v72, v34
	v_add_f32_e32 v0, v119, v0
	v_exp_f32_e32 v123, v1
	v_sub_f32_e32 v1, v73, v34
	v_add_f32_e32 v0, v120, v0
	v_exp_f32_e32 v124, v1
	v_sub_f32_e32 v1, v74, v34
	v_add_f32_e32 v0, v121, v0
	v_exp_f32_e32 v125, v1
	v_sub_f32_e32 v1, v75, v34
	v_add_f32_e32 v0, v122, v0
	v_exp_f32_e32 v126, v1
	v_sub_f32_e32 v1, v76, v34
	v_add_f32_e32 v0, v123, v0
	v_exp_f32_e32 v127, v1
	v_sub_f32_e32 v1, v77, v34
	v_add_f32_e32 v0, v124, v0
	v_exp_f32_e32 v128, v1
	v_sub_f32_e32 v1, v78, v34
	v_add_f32_e32 v0, v125, v0
	v_exp_f32_e32 v129, v1
	v_sub_f32_e32 v1, v79, v34
	v_add_f32_e32 v0, v126, v0
	v_exp_f32_e32 v130, v1
	v_sub_f32_e32 v1, v48, v34
	v_add_f32_e32 v0, v127, v0
	v_exp_f32_e32 v131, v1
	v_sub_f32_e32 v1, v49, v34
	v_add_f32_e32 v0, v128, v0
	v_exp_f32_e32 v132, v1
	v_sub_f32_e32 v1, v50, v34
	v_add_f32_e32 v0, v129, v0
	v_exp_f32_e32 v133, v1
	v_sub_f32_e32 v1, v51, v34
	v_add_f32_e32 v0, v130, v0
	v_exp_f32_e32 v134, v1
	v_sub_f32_e32 v1, v52, v34
	v_add_f32_e32 v0, v131, v0
	v_exp_f32_e32 v135, v1
	v_sub_f32_e32 v1, v53, v34
	v_add_f32_e32 v0, v132, v0
	v_exp_f32_e32 v136, v1
	v_sub_f32_e32 v1, v54, v34
	v_add_f32_e32 v0, v133, v0
	v_exp_f32_e32 v137, v1
	v_sub_f32_e32 v1, v55, v34
	v_add_f32_e32 v0, v134, v0
	v_exp_f32_e32 v138, v1
	v_sub_f32_e32 v1, v56, v34
	v_add_f32_e32 v0, v135, v0
	v_exp_f32_e32 v139, v1
	v_sub_f32_e32 v1, v57, v34
	v_add_f32_e32 v0, v136, v0
	v_exp_f32_e32 v140, v1
	v_sub_f32_e32 v1, v58, v34
	v_add_f32_e32 v0, v137, v0
	v_exp_f32_e32 v141, v1
	v_sub_f32_e32 v1, v59, v34
	v_add_f32_e32 v0, v138, v0
	v_exp_f32_e32 v142, v1
	v_sub_f32_e32 v1, v60, v34
	v_add_f32_e32 v0, v139, v0
	v_exp_f32_e32 v143, v1
	v_sub_f32_e32 v1, v61, v34
	v_add_f32_e32 v0, v140, v0
; __device__ __forceinline__ float shfl_idx(float v, int srclane) { return __int_as_float(__builtin_amdgcn_ds_bpermute(srclane << 2, __float_as_int(v))); }
; __device__ __forceinline__ int v_st2(int k, int c) { const int kk = (k & ~0xC) | ((k & 4) << 1) | ((k & 8) >> 1); return ((kk >> 3) * 2 + (c >> 5)) * 512 + ((kk & 7) * 32 + (c & 31)) * 2; }
; __device__ __forceinline__ int v_rd_base(int lane) { return ((lane & 3) << 3) | (((lane >> 2) & 3) << 6) | (((lane >> 4) & 1) << 5) | (((lane >> 5) & 1) << 8); }
; __device__ __forceinline__ void dil_wave_item(const bf16* __restrict__ qkv, bf16* __restrict__ odil, float* __restrict__ lse,
;                               int pat, int g  , int head, char* wl  , const int W) {
;     ...
;   for (int kb = 0; kb < 5; ++kb)
; #pragma unroll
;     for (int r = 0; r < 16; ++r) { const float e = __builtin_amdgcn_exp2f(sc[kb][r] - mx); sc[kb][r] = e; ls += e; }
;   ls += shfl_idx(ls, lane ^ 32);
;   f32x16 o0 = {}, o1 = {};
;   const int vb = (int)(uintptr_t)wl + v_rd_base(lane);
; #pragma unroll
;   for (int kb = 0; kb < 5; ++kb) {
;     bf16x8 vr[4];
; #pragma unroll
;     for (int i = 0; i < 4; ++i) {
;       const int key = i * 8 + (lane >> 3);
;       int kc = i0 - 64 + kb * 32 + key; kc = min(max(kc, 0), L - 1);
;       vr[i] = *reinterpret_cast<const bf16x8*>(qkv + (size_t)(tbase + kc * dil) * LDQ + 2560 + head * 64 + (lane & 7) * 8);
;     }
; #pragma unroll
;     for (int i = 0; i < 4; ++i) *reinterpret_cast<bf16x8*>(wl + v_st2(i * 8 + (lane >> 3), (lane & 7) * 8)) = vr[i];
	v_exp_f32_e32 v144, v1
	v_sub_f32_e32 v1, v62, v34
	v_add_f32_e32 v0, v141, v0
	v_exp_f32_e32 v145, v1
	v_sub_f32_e32 v1, v63, v34
	v_add_f32_e32 v0, v142, v0
	v_exp_f32_e32 v146, v1
	v_sub_f32_e32 v1, v32, v34
	v_add_f32_e32 v0, v143, v0
	v_exp_f32_e32 v56, v1
	v_sub_f32_e32 v1, v33, v34
	v_add_f32_e32 v0, v144, v0
	v_exp_f32_e32 v57, v1
	v_sub_f32_e32 v1, v96, v34
	v_add_f32_e32 v0, v145, v0
	v_exp_f32_e32 v60, v1
	v_sub_f32_e32 v1, v35, v34
	v_add_f32_e32 v0, v146, v0
	v_exp_f32_e32 v65, v1
	v_sub_f32_e32 v1, v36, v34
	v_add_f32_e32 v0, v56, v0
	v_exp_f32_e32 v69, v1
	v_sub_f32_e32 v1, v37, v34
	v_add_f32_e32 v0, v57, v0
	v_exp_f32_e32 v71, v1
	v_sub_f32_e32 v1, v38, v34
	v_add_f32_e32 v0, v60, v0
	v_exp_f32_e32 v75, v1
	v_sub_f32_e32 v1, v39, v34
	v_add_f32_e32 v0, v65, v0
	v_exp_f32_e32 v78, v1
	v_sub_f32_e32 v1, v40, v34
	v_add_f32_e32 v0, v69, v0
	v_exp_f32_e32 v72, v1
	v_sub_f32_e32 v1, v41, v34
	v_add_f32_e32 v0, v71, v0
	v_exp_f32_e32 v76, v1
	v_sub_f32_e32 v1, v42, v34
	v_add_f32_e32 v0, v75, v0
	v_exp_f32_e32 v79, v1
	v_sub_f32_e32 v1, v43, v34
	v_add_f32_e32 v0, v78, v0
	v_exp_f32_e32 v93, v1
	v_sub_f32_e32 v1, v44, v34
	v_add_f32_e32 v0, v72, v0
	v_exp_f32_e32 v94, v1
	v_sub_f32_e32 v1, v45, v34
	v_add_f32_e32 v0, v76, v0
	v_exp_f32_e32 v95, v1
	v_sub_f32_e32 v1, v46, v34
	v_add_f32_e32 v0, v79, v0
	v_exp_f32_e32 v96, v1
	v_sub_f32_e32 v1, v47, v34
	v_add_f32_e32 v0, v93, v0
	v_exp_f32_e32 v97, v1
	v_sub_f32_e32 v1, v16, v34
	v_add_f32_e32 v0, v94, v0
	v_exp_f32_e32 v35, v1
	v_sub_f32_e32 v1, v17, v34
	v_add_f32_e32 v0, v95, v0
	v_exp_f32_e32 v36, v1
	v_sub_f32_e32 v1, v18, v34
	v_add_f32_e32 v0, v96, v0
	v_exp_f32_e32 v37, v1
	v_sub_f32_e32 v1, v19, v34
	v_add_f32_e32 v0, v97, v0
	v_exp_f32_e32 v38, v1
	v_sub_f32_e32 v1, v20, v34
	v_add_f32_e32 v0, v35, v0
	v_exp_f32_e32 v42, v1
	v_sub_f32_e32 v1, v21, v34
	v_add_f32_e32 v0, v36, v0
	v_exp_f32_e32 v43, v1
	v_sub_f32_e32 v1, v22, v34
	v_add_f32_e32 v0, v37, v0
	v_exp_f32_e32 v45, v1
	v_sub_f32_e32 v1, v23, v34
	v_add_f32_e32 v0, v38, v0
	v_exp_f32_e32 v47, v1
	v_sub_f32_e32 v1, v24, v34
	v_add_f32_e32 v0, v42, v0
	v_exp_f32_e32 v44, v1
	v_sub_f32_e32 v1, v25, v34
	v_add_f32_e32 v0, v43, v0
	v_exp_f32_e32 v46, v1
	v_sub_f32_e32 v1, v26, v34
	v_add_f32_e32 v0, v45, v0
	v_exp_f32_e32 v48, v1
	v_sub_f32_e32 v1, v27, v34
	v_add_f32_e32 v0, v47, v0
	v_exp_f32_e32 v49, v1
	v_add_f32_e32 v0, v44, v0
	v_add_f32_e32 v0, v46, v0
	v_add_f32_e32 v0, v48, v0
	v_bfe_u32 v17, v92, 3, 3
	v_add_f32_e32 v16, v49, v0
	v_sub_f32_e32 v0, v28, v34
	v_or_b32_e32 v10, s78, v17
	v_exp_f32_e32 v50, v0
	v_sub_f32_e32 v0, v29, v34
	v_subrev_u32_e32 v39, 64, v10
	v_lshlrev_b32_e32 v18, 3, v92
	v_exp_f32_e32 v51, v0
	v_and_b32_e32 v2, 56, v18
	v_max_i32_e32 v0, 0, v39
	v_min_u32_e32 v0, s6, v0
	v_lshlrev_b32_e32 v32, 1, v2
	v_subrev_u32_e32 v2, 56, v10
	v_lshlrev_b32_e32 v0, s71, v0
	v_max_i32_e32 v2, 0, v2
	v_add_u32_e32 v0, s79, v0
	v_min_u32_e32 v2, s6, v2
	v_subrev_u32_e32 v8, 48, v10
	v_mad_i64_i32 v[0:1], s[4:5], v0, s62, v[84:85]
	v_lshlrev_b32_e32 v2, s71, v2
	v_max_i32_e32 v8, 0, v8
	v_lshl_add_u64 v[0:1], v[0:1], 0, s[74:75]
	v_mov_b32_e32 v33, v83
	v_add_u32_e32 v2, s79, v2
	v_min_u32_e32 v8, s6, v8
	v_subrev_u32_e32 v10, 40, v10
	v_lshl_add_u64 v[0:1], v[0:1], 0, v[32:33]
	v_mad_i64_i32 v[2:3], s[4:5], v2, s62, v[84:85]
	v_lshlrev_b32_e32 v8, s71, v8
	v_max_i32_e32 v10, 0, v10
	v_add_co_u32_e32 v0, vcc, s63, v0
	v_lshl_add_u64 v[2:3], v[2:3], 0, s[74:75]
	v_add_u32_e32 v8, s79, v8
	v_min_u32_e32 v10, s6, v10
	v_addc_co_u32_e32 v1, vcc, 0, v1, vcc
	v_lshl_add_u64 v[2:3], v[2:3], 0, v[32:33]
	v_mad_i64_i32 v[8:9], s[4:5], v8, s62, v[84:85]
	v_lshlrev_b32_e32 v10, s71, v10
	v_add_co_u32_e32 v4, vcc, s63, v2
	v_lshl_add_u64 v[8:9], v[8:9], 0, s[74:75]
	v_add_u32_e32 v10, s79, v10
	v_addc_co_u32_e32 v5, vcc, 0, v3, vcc
	v_lshl_add_u64 v[8:9], v[8:9], 0, v[32:33]
	v_mad_i64_i32 v[10:11], s[4:5], v10, s62, v[84:85]
	v_add_co_u32_e32 v8, vcc, s63, v8
	v_lshl_add_u64 v[10:11], v[10:11], 0, s[74:75]
	s_nop 0
	v_addc_co_u32_e32 v9, vcc, 0, v9, vcc
	v_lshl_add_u64 v[10:11], v[10:11], 0, v[32:33]
	v_add_co_u32_e32 v12, vcc, s63, v10
	s_nop 0
	v_addc_co_u32_e32 v13, vcc, 0, v11, vcc
	s_nop 0
	v_sub_f32_e32 v19, v30, v34
	v_exp_f32_e32 v147, v19
	v_sub_f32_e32 v19, v31, v34
	v_exp_f32_e32 v148, v19
	v_sub_f32_e32 v19, v98, v34
	v_add_f32_e32 v16, v50, v16
	v_exp_f32_e32 v52, v19
	v_sub_f32_e32 v19, v99, v34
	v_add_f32_e32 v16, v51, v16
	v_exp_f32_e32 v53, v19
	v_sub_f32_e32 v19, v100, v34
	v_add_f32_e32 v16, v147, v16
	v_exp_f32_e32 v54, v19
	v_sub_f32_e32 v19, v101, v34
	v_add_f32_e32 v16, v148, v16
	v_exp_f32_e32 v55, v19
	v_sub_f32_e32 v19, v102, v34
	v_add_f32_e32 v16, v52, v16
	v_exp_f32_e32 v58, v19
	v_sub_f32_e32 v19, v103, v34
	v_add_f32_e32 v16, v53, v16
	v_exp_f32_e32 v61, v19
	v_sub_f32_e32 v19, v104, v34
	v_add_f32_e32 v16, v54, v16
	v_exp_f32_e32 v63, v19
	v_sub_f32_e32 v19, v105, v34
	v_add_f32_e32 v16, v55, v16
	v_exp_f32_e32 v66, v19
	v_sub_f32_e32 v19, v106, v34
	v_add_f32_e32 v16, v58, v16
	v_exp_f32_e32 v59, v19
	v_sub_f32_e32 v19, v107, v34
	v_add_f32_e32 v16, v61, v16
	v_exp_f32_e32 v62, v19
	v_sub_f32_e32 v19, v108, v34
	v_add_f32_e32 v16, v63, v16
	v_exp_f32_e32 v64, v19
	v_sub_f32_e32 v19, v109, v34
	v_add_f32_e32 v16, v66, v16
	v_exp_f32_e32 v67, v19
	v_sub_f32_e32 v19, v110, v34
	v_add_f32_e32 v16, v59, v16
	v_exp_f32_e32 v70, v19
	v_sub_f32_e32 v19, v111, v34
	v_add_f32_e32 v16, v62, v16
	v_exp_f32_e32 v73, v19
	v_sub_f32_e32 v19, v112, v34
	v_add_f32_e32 v16, v64, v16
	v_exp_f32_e32 v74, v19
	v_sub_f32_e32 v19, v113, v34
	v_add_f32_e32 v16, v67, v16
	v_exp_f32_e32 v77, v19
	v_add_f32_e32 v16, v70, v16
	v_add_f32_e32 v16, v73, v16
	v_add_f32_e32 v16, v74, v16
	v_lshlrev_b32_e32 v19, 4, v92
	v_add_f32_e32 v40, v77, v16
	v_lshlrev_b32_e32 v16, 3, v87
	v_and_b32_e32 v20, 0xc0, v19
	v_lshlrev_b32_e32 v21, 1, v92
	v_and_or_b32 v20, v16, 24, v20
	v_and_b32_e32 v21, 32, v21
	v_and_b32_e32 v16, 0x100, v16
	v_or3_b32 v16, v20, v21, v16
	v_add_u32_e32 v68, s55, v16
	v_bfe_u32 v16, v18, 5, 1
	v_and_b32_e32 v18, 48, v19
	v_lshrrev_b32_e32 v19, 4, v92
	v_and_or_b32 v16, v19, 2, v16
	v_lshlrev_b32_e32 v17, 6, v17
	v_and_or_b32 v19, v17, s69, v18
	v_lshl_add_u32 v16, v16, 9, s55
	v_add_u32_e32 v149, v16, v19
	ds_bpermute_b32 v41, v114, v40
	s_waitcnt vmcnt(16)
; #define SBAR() __builtin_amdgcn_sched_barrier(0)
; __device__ __forceinline__ int v_st2(int k, int c) { const int kk = (k & ~0xC) | ((k & 4) << 1) | ((k & 8) >> 1); return ((kk >> 3) * 2 + (c >> 5)) * 512 + ((kk & 7) * 32 + (c & 31)) * 2; }
; __device__ __forceinline__ void dil_wave_item(const bf16* __restrict__ qkv, bf16* __restrict__ odil, float* __restrict__ lse,
;                               int pat, int g  , int head, char* wl  , const int W) {
;     ...
; #pragma unroll
;   for (int kb = 0; kb < 5; ++kb) {
;     bf16x8 vr[4];
; #pragma unroll
;     for (int i = 0; i < 4; ++i) {
;       const int key = i * 8 + (lane >> 3);
;       int kc = i0 - 64 + kb * 32 + key; kc = min(max(kc, 0), L - 1);
;       vr[i] = *reinterpret_cast<const bf16x8*>(qkv + (size_t)(tbase + kc * dil) * LDQ + 2560 + head * 64 + (lane & 7) * 8);
;     }
; #pragma unroll
;     for (int i = 0; i < 4; ++i) *reinterpret_cast<bf16x8*>(wl + v_st2(i * 8 + (lane >> 3), (lane & 7) * 8)) = vr[i];
;     bf16x8 pa0, pa1;
;     PK4(sc[kb], 0, pa0); PK4(sc[kb], 8, pa1);
;     asm volatile("s_waitcnt lgkmcnt(0)" ::: "memory");
;     const s16x4 a0 = tr_read<v_rd_off2(0, 0, 0)>(vb), b0 = tr_read<v_rd_off2(0, 0, 1)>(vb), a1 = tr_read<v_rd_off2(0, 1, 0)>(vb), b1 = tr_read<v_rd_off2(0, 1, 1)>(vb);
;     const s16x4 c0 = tr_read<v_rd_off2(1, 0, 0)>(vb), d0_ = tr_read<v_rd_off2(1, 0, 1)>(vb), c1 = tr_read<v_rd_off2(1, 1, 0)>(vb), d1 = tr_read<v_rd_off2(1, 1, 1)>(vb);
;     asm volatile("s_waitcnt lgkmcnt(0)" ::: "memory"); SBAR();
;     o0 = __builtin_amdgcn_mfma_f32_32x32x16_bf16(pa0, PKV(a0, b0), o0, 0, 0, 0);
;     o0 = __builtin_amdgcn_mfma_f32_32x32x16_bf16(pa1, PKV(a1, b1), o0, 0, 0, 0);
;     o1 = __builtin_amdgcn_mfma_f32_32x32x16_bf16(pa0, PKV(c0, d0_), o1, 0, 0, 0);
;     o1 = __builtin_amdgcn_mfma_f32_32x32x16_bf16(pa1, PKV(c1, d1), o1, 0, 0, 0);
;     SBAR();
;   }
;   if (hi == 0) lse[((size_t)pat * T + tbase + (i0 + r32) * dil) * 8 + head] = mx + __log2f(ls);
	ds_write_b128 v149, v[152:155]
	v_or3_b32 v0, v17, v18, s61
	v_add_u32_e32 v150, v16, v0
	ds_write_b128 v150, v[156:159]
	ds_write_b128 v149, v[160:163] offset:2048
	ds_write_b128 v150, v[164:167] offset:2048
	v_cvt_pk_bf16_f32 v16, v115, v116
	v_cvt_pk_bf16_f32 v17, v117, v118
	v_cvt_pk_bf16_f32 v18, v119, v120
	v_cvt_pk_bf16_f32 v19, v121, v122
	v_cvt_pk_bf16_f32 v98, v123, v124
	v_cvt_pk_bf16_f32 v99, v125, v126
	v_cvt_pk_bf16_f32 v100, v127, v128
	v_cvt_pk_bf16_f32 v101, v129, v130
	s_waitcnt lgkmcnt(0)
	ds_read_b64_tr_b16 v[0:1], v68 offset:0
	ds_read_b64_tr_b16 v[2:3], v68 offset:0x400
	ds_read_b64_tr_b16 v[20:21], v68 offset:0x800
	ds_read_b64_tr_b16 v[22:23], v68 offset:0xc00
	ds_read_b64_tr_b16 v[24:25], v68 offset:0x200
	ds_read_b64_tr_b16 v[26:27], v68 offset:0x600
	ds_read_b64_tr_b16 v[102:103], v68 offset:0xa00
	ds_read_b64_tr_b16 v[104:105], v68 offset:0xe00
	s_waitcnt lgkmcnt(0)
	s_nop 0
	v_permlane32_swap_b32_e32 v16, v18
	v_permlane32_swap_b32_e32 v17, v19
	v_permlane32_swap_b32_e32 v98, v100
	v_permlane32_swap_b32_e32 v99, v101
	v_mfma_f32_32x32x16_bf16 v[0:15], v[0:3], v[16:19], 0
	s_nop 0
	v_mfma_f32_32x32x16_bf16 v[0:15], v[20:23], v[98:101], v[0:15]
	v_mfma_f32_32x32x16_bf16 v[16:31], v[24:27], v[16:19], 0
	v_mfma_f32_32x32x16_bf16 v[16:31], v[102:105], v[98:101], v[16:31]
	s_waitcnt vmcnt(12)
	ds_write_b128 v149, v[168:171]
	ds_write_b128 v150, v[172:175]
	ds_write_b128 v149, v[176:179] offset:2048
	ds_write_b128 v150, v[180:183] offset:2048
	v_cvt_pk_bf16_f32 v98, v131, v132
	v_cvt_pk_bf16_f32 v99, v133, v134
	v_cvt_pk_bf16_f32 v100, v135, v136
	v_cvt_pk_bf16_f32 v101, v137, v138
	v_cvt_pk_bf16_f32 v102, v139, v140
	v_cvt_pk_bf16_f32 v103, v141, v142
	v_cvt_pk_bf16_f32 v104, v143, v144
	v_cvt_pk_bf16_f32 v105, v145, v146
	s_waitcnt lgkmcnt(0)
	ds_read_b64_tr_b16 v[106:107], v68 offset:0
	ds_read_b64_tr_b16 v[108:109], v68 offset:0x400
	ds_read_b64_tr_b16 v[110:111], v68 offset:0x800
	ds_read_b64_tr_b16 v[112:113], v68 offset:0xc00
	ds_read_b64_tr_b16 v[114:115], v68 offset:0x200
	ds_read_b64_tr_b16 v[116:117], v68 offset:0x600
	ds_read_b64_tr_b16 v[118:119], v68 offset:0xa00
	ds_read_b64_tr_b16 v[120:121], v68 offset:0xe00
	s_waitcnt lgkmcnt(0)
	s_nop 0
	v_permlane32_swap_b32_e32 v98, v100
	v_permlane32_swap_b32_e32 v99, v101
	v_permlane32_swap_b32_e32 v102, v104
	v_permlane32_swap_b32_e32 v103, v105
	v_mfma_f32_32x32x16_bf16 v[0:15], v[106:109], v[98:101], v[0:15]
	v_mfma_f32_32x32x16_bf16 v[16:31], v[114:117], v[98:101], v[16:31]
	v_mfma_f32_32x32x16_bf16 v[0:15], v[110:113], v[102:105], v[0:15]
	v_mfma_f32_32x32x16_bf16 v[16:31], v[118:121], v[102:105], v[16:31]
	s_waitcnt vmcnt(8)
	ds_write_b128 v149, v[184:187]
	ds_write_b128 v150, v[188:191]
	ds_write_b128 v149, v[192:195] offset:2048
	ds_write_b128 v150, v[196:199] offset:2048
	v_cvt_pk_bf16_f32 v98, v56, v57
	v_cvt_pk_bf16_f32 v99, v60, v65
	v_cvt_pk_bf16_f32 v100, v69, v71
	v_cvt_pk_bf16_f32 v101, v75, v78
	v_cvt_pk_bf16_f32 v92, v72, v76
	v_cvt_pk_bf16_f32 v93, v79, v93
	v_cvt_pk_bf16_f32 v94, v94, v95
	v_cvt_pk_bf16_f32 v95, v96, v97
	s_waitcnt lgkmcnt(0)
	ds_read_b64_tr_b16 v[102:103], v68 offset:0
	ds_read_b64_tr_b16 v[104:105], v68 offset:0x400
	ds_read_b64_tr_b16 v[106:107], v68 offset:0x800
	ds_read_b64_tr_b16 v[108:109], v68 offset:0xc00
	ds_read_b64_tr_b16 v[110:111], v68 offset:0x200
	ds_read_b64_tr_b16 v[112:113], v68 offset:0x600
	ds_read_b64_tr_b16 v[114:115], v68 offset:0xa00
	ds_read_b64_tr_b16 v[116:117], v68 offset:0xe00
	s_waitcnt lgkmcnt(0)
	s_nop 0
	v_permlane32_swap_b32_e32 v98, v100
	v_permlane32_swap_b32_e32 v99, v101
	v_permlane32_swap_b32_e32 v92, v94
	v_permlane32_swap_b32_e32 v93, v95
	v_mfma_f32_32x32x16_bf16 v[0:15], v[102:105], v[98:101], v[0:15]
	v_mfma_f32_32x32x16_bf16 v[16:31], v[110:113], v[98:101], v[16:31]
	v_mfma_f32_32x32x16_bf16 v[0:15], v[106:109], v[92:95], v[0:15]
	v_mfma_f32_32x32x16_bf16 v[16:31], v[114:117], v[92:95], v[16:31]
	s_waitcnt vmcnt(4)
	ds_write_b128 v149, v[200:203]
	ds_write_b128 v150, v[204:207]
	ds_write_b128 v149, v[208:211] offset:2048
	ds_write_b128 v150, v[212:215] offset:2048
	v_cvt_pk_bf16_f32 v92, v35, v36
	v_cvt_pk_bf16_f32 v93, v37, v38
	v_cvt_pk_bf16_f32 v94, v42, v43
	v_cvt_pk_bf16_f32 v95, v45, v47
	v_cvt_pk_bf16_f32 v42, v44, v46
	v_cvt_pk_bf16_f32 v43, v48, v49
	v_cvt_pk_bf16_f32 v44, v50, v51
	v_cvt_pk_bf16_f32 v45, v147, v148
	s_waitcnt lgkmcnt(0)
	ds_read_b64_tr_b16 v[46:47], v68 offset:0
	ds_read_b64_tr_b16 v[48:49], v68 offset:0x400
	ds_read_b64_tr_b16 v[96:97], v68 offset:0x800
	ds_read_b64_tr_b16 v[98:99], v68 offset:0xc00
	ds_read_b64_tr_b16 v[100:101], v68 offset:0x200
	ds_read_b64_tr_b16 v[102:103], v68 offset:0x600
	ds_read_b64_tr_b16 v[104:105], v68 offset:0xa00
	ds_read_b64_tr_b16 v[106:107], v68 offset:0xe00
	s_waitcnt lgkmcnt(0)
	s_nop 0
	v_permlane32_swap_b32_e32 v92, v94
	v_permlane32_swap_b32_e32 v93, v95
	v_permlane32_swap_b32_e32 v42, v44
	v_permlane32_swap_b32_e32 v43, v45
	v_mfma_f32_32x32x16_bf16 v[0:15], v[46:49], v[92:95], v[0:15]
	v_mfma_f32_32x32x16_bf16 v[16:31], v[100:103], v[92:95], v[16:31]
	v_mfma_f32_32x32x16_bf16 v[0:15], v[96:99], v[42:45], v[0:15]
	v_mfma_f32_32x32x16_bf16 v[16:31], v[104:107], v[42:45], v[16:31]
	s_waitcnt vmcnt(0)
	ds_write_b128 v149, v[216:219]
	ds_write_b128 v150, v[220:223]
	ds_write_b128 v149, v[224:227] offset:2048
	ds_write_b128 v150, v[228:231] offset:2048
	v_cvt_pk_bf16_f32 v36, v52, v53
	v_cvt_pk_bf16_f32 v37, v54, v55
	v_cvt_pk_bf16_f32 v38, v58, v61
	v_cvt_pk_bf16_f32 v39, v63, v66
	v_cvt_pk_bf16_f32 v42, v59, v62
	v_cvt_pk_bf16_f32 v43, v64, v67
	v_cvt_pk_bf16_f32 v44, v70, v73
	v_cvt_pk_bf16_f32 v45, v74, v77
	s_waitcnt lgkmcnt(0)
	ds_read_b64_tr_b16 v[46:47], v68 offset:0
	ds_read_b64_tr_b16 v[48:49], v68 offset:0x400
	ds_read_b64_tr_b16 v[50:51], v68 offset:0x800
	ds_read_b64_tr_b16 v[52:53], v68 offset:0xc00
	ds_read_b64_tr_b16 v[54:55], v68 offset:0x200
	ds_read_b64_tr_b16 v[56:57], v68 offset:0x600
	ds_read_b64_tr_b16 v[58:59], v68 offset:0xa00
	ds_read_b64_tr_b16 v[60:61], v68 offset:0xe00
	s_waitcnt lgkmcnt(0)
	s_nop 0
	v_permlane32_swap_b32_e32 v36, v38
	v_permlane32_swap_b32_e32 v37, v39
	v_permlane32_swap_b32_e32 v42, v44
	v_permlane32_swap_b32_e32 v43, v45
	v_mfma_f32_32x32x16_bf16 v[0:15], v[46:49], v[36:39], v[0:15]
	v_mfma_f32_32x32x16_bf16 v[16:31], v[54:57], v[36:39], v[16:31]
	v_mfma_f32_32x32x16_bf16 v[0:15], v[50:53], v[42:45], v[0:15]
	v_mfma_f32_32x32x16_bf16 v[16:31], v[58:61], v[42:45], v[16:31]
	v_cmp_lt_u32_e32 vcc, 31, v87
	s_and_saveexec_b64 s[4:5], vcc
	s_xor_b64 s[4:5], exec, s[4:5]
	s_ashr_i32 s11, s10, 31
	s_lshl_b64 s[6:7], s[10:11], 15
	s_ashr_i32 s11, s79, 31
	s_add_u32 s6, s6, s79
	s_addc_u32 s7, s7, s11
	s_or_saveexec_b64 s[4:5], s[4:5]
	s_waitcnt lgkmcnt(14)
	v_add_f32_e32 v35, v40, v41
	v_mov_b64_e32 v[32:33], s[6:7]
	s_xor_b64 exec, exec, s[4:5]
	s_cbranch_execz .LBB0_82
; __device__ __forceinline__ void dil_wave_item(const bf16* __restrict__ qkv, bf16* __restrict__ odil, float* __restrict__ lse,
;                               int pat, int g  , int head, char* wl  , const int W) {
;     ...
;   if (hi == 0) lse[((size_t)pat * T + tbase + (i0 + r32) * dil) * 8 + head] = mx + __log2f(ls);
	v_log_f32_e32 v32, v35
	s_ashr_i32 s11, s10, 31
	s_ashr_i32 s66, s79, 31
	s_lshl_b64 s[6:7], s[10:11], 15
	s_add_u32 s6, s6, s79
	s_addc_u32 s7, s7, s66
	v_ashrrev_i32_e32 v87, 31, v86
	v_add_f32_e32 v34, v34, v32
	v_lshl_add_u64 v[32:33], s[6:7], 0, v[86:87]
	v_lshlrev_b64 v[32:33], 5, v[32:33]
	v_lshl_add_u64 v[32:33], s[72:73], 0, v[32:33]
	global_store_dword v[32:33], v34, off
	v_mov_b64_e32 v[32:33], s[6:7]
	s_branch .LBB0_82

; __device__ __forceinline__ float shfl_idx(float v, int srclane) { return __int_as_float(__builtin_amdgcn_ds_bpermute(srclane << 2, __float_as_int(v))); }
; __device__ __forceinline__ int crow(int r, int hi) { return (r & 3) + 8 * (r >> 2) + 4 * hi; }
; __device__ __forceinline__ void dil_wave_item(const bf16* __restrict__ qkv, bf16* __restrict__ odil, float* __restrict__ lse,
;                               int pat, int g  , int head, char* wl  , const int W) {
;     ...
;   const float rl = __builtin_amdgcn_rcpf(ls);
; #pragma unroll
;   for (int r = 0; r < 16; ++r) {
;     const int q = crow(r, hi);
;     const float rq = shfl_idx(rl, q);
;     bf16* dst = odil + ((size_t)pat * T + tbase + (i0 + q) * dil) * 512 + head * 64 + r32;
;     dst[0] = __float2bfloat16(o0[r] * rq); dst[32] = __float2bfloat16(o1[r] * rq);
;   }
.LBB0_293:
	s_or_b64 exec, exec, s[6:7]
	v_rcp_f32_e32 v38, v35
	v_or_b32_e32 v36, s41, v102
	v_lshlrev_b32_e32 v36, s40, v36
	v_ashrrev_i32_e32 v37, 31, v36
	v_lshl_add_u64 v[36:37], v[32:33], 0, v[36:37]
	v_lshlrev_b32_e32 v34, 1, v80
	v_mov_b32_e32 v35, v95
	v_lshlrev_b64 v[36:37], 10, v[36:37]
	v_lshl_add_u64 v[34:35], s[76:77], 0, v[34:35]
	s_add_i32 s27, s27, s33
	v_lshl_add_u64 v[36:37], v[34:35], 0, v[36:37]
	v_pk_mul_f32 v[0:1], v[0:1], v[38:39] op_sel_hi:[1,0]
	v_pk_mul_f32 v[2:3], v[2:3], v[38:39] op_sel_hi:[1,0]
	v_cvt_pk_bf16_f32 v0, v0, v1
	v_cvt_pk_bf16_f32 v1, v2, v3
	global_store_dwordx2 v[36:37], v[0:1], off
	v_pk_mul_f32 v[4:5], v[4:5], v[38:39] op_sel_hi:[1,0]
	v_pk_mul_f32 v[6:7], v[6:7], v[38:39] op_sel_hi:[1,0]
	v_cvt_pk_bf16_f32 v4, v4, v5
	v_cvt_pk_bf16_f32 v5, v6, v7
	global_store_dwordx2 v[36:37], v[4:5], off offset:16
	v_pk_mul_f32 v[8:9], v[8:9], v[38:39] op_sel_hi:[1,0]
	v_pk_mul_f32 v[10:11], v[10:11], v[38:39] op_sel_hi:[1,0]
	v_cvt_pk_bf16_f32 v8, v8, v9
	v_cvt_pk_bf16_f32 v9, v10, v11
	global_store_dwordx2 v[36:37], v[8:9], off offset:32
	v_pk_mul_f32 v[12:13], v[12:13], v[38:39] op_sel_hi:[1,0]
	v_pk_mul_f32 v[14:15], v[14:15], v[38:39] op_sel_hi:[1,0]
	v_cvt_pk_bf16_f32 v12, v12, v13
	v_cvt_pk_bf16_f32 v13, v14, v15
	global_store_dwordx2 v[36:37], v[12:13], off offset:48
	v_pk_mul_f32 v[16:17], v[16:17], v[38:39] op_sel_hi:[1,0]
	v_pk_mul_f32 v[18:19], v[18:19], v[38:39] op_sel_hi:[1,0]
	v_cvt_pk_bf16_f32 v16, v16, v17
	v_cvt_pk_bf16_f32 v17, v18, v19
	global_store_dwordx2 v[36:37], v[16:17], off offset:64
	v_pk_mul_f32 v[20:21], v[20:21], v[38:39] op_sel_hi:[1,0]
	v_pk_mul_f32 v[22:23], v[22:23], v[38:39] op_sel_hi:[1,0]
	v_cvt_pk_bf16_f32 v20, v20, v21
	v_cvt_pk_bf16_f32 v21, v22, v23
	global_store_dwordx2 v[36:37], v[20:21], off offset:80
	v_pk_mul_f32 v[24:25], v[24:25], v[38:39] op_sel_hi:[1,0]
	v_pk_mul_f32 v[26:27], v[26:27], v[38:39] op_sel_hi:[1,0]
	v_cvt_pk_bf16_f32 v24, v24, v25
	v_cvt_pk_bf16_f32 v25, v26, v27
	global_store_dwordx2 v[36:37], v[24:25], off offset:96
	v_pk_mul_f32 v[28:29], v[28:29], v[38:39] op_sel_hi:[1,0]
	v_pk_mul_f32 v[30:31], v[30:31], v[38:39] op_sel_hi:[1,0]
	v_cvt_pk_bf16_f32 v28, v28, v29
	v_cvt_pk_bf16_f32 v29, v30, v31
	global_store_dwordx2 v[36:37], v[28:29], off offset:112
	s_cmpk_gt_i32 s27, 0xbff
	s_cbranch_scc1 .LBB0_305

; #define otid() (W * 64 + olane())
; __device__ __forceinline__ void dil_wave_item(const bf16* __restrict__ qkv, bf16* __restrict__ odil, float* __restrict__ lse,
;                               int pat, int g  , int head, char* wl  , const int W) {
;   const int lane = otid() & 63, r32 = lane & 31, hi = lane >> 5;
;   const int dil = (pat == 0) ? 1 : (pat == 1 ? 4 : 16);
;   int seq0, slen, gl;
;   if (g < 256) { seq0 = 0; slen = 8192; gl = g; } else if (g < 512) { seq0 = 8192; slen = 8192; gl = g - 256; } else { seq0 = 16384; slen = 16384; gl = g - 512; }
;   const int L = slen / dil, tpr = L / 32, res = gl / tpr, i0 = (gl % tpr) * 32;
;   const int tbase = seq0 + res;
;   bf16x8 qr[4];
;   { const bf16* qp = qkv + (size_t)(tbase + (i0 + r32) * dil) * LDQ + 1536 + head * 64 + hi * 8;
; #pragma unroll
;     for (int d0 = 0; d0 < 4; ++d0) qr[d0] = *reinterpret_cast<const bf16x8*>(qp + d0 * 16); }
;   f32x16 sc[5];
; #pragma unroll
;   for (int kb = 0; kb < 5; ++kb) {
;     int kc = i0 - 64 + kb * 32 + r32; kc = min(max(kc, 0), L - 1);
;     const bf16* kp = qkv + (size_t)(tbase + kc * dil) * LDQ + 2048 + head * 64 + hi * 8;
;     f32x16 a = {};
; #pragma unroll
;     for (int d0 = 0; d0 < 4; ++d0) {
;       bf16x8 kf = *reinterpret_cast<const bf16x8*>(kp + d0 * 16);
;       a = __builtin_amdgcn_mfma_f32_32x32x16_bf16(kf, qr[d0], a, 0, 0, 0);
;     }
;     sc[kb] = a;
.LBB0_301:
	s_add_i32 s8, s27, 0x3ff
	s_and_b32 s9, s27, 0xfffffc00
	s_cmpk_eq_i32 s9, 0x400
	s_cselect_b32 s9, 2, 4
	s_cmpk_gt_u32 s8, 0x7fe
	s_cselect_b32 s40, s9, 0
	s_lshr_b32 s20, s7, s40
	s_lshr_b32 s7, s20, 5
	s_sext_i32_i16 s9, s7
	v_cvt_f32_i32_e32 v1, s9
	s_sext_i32_i16 s8, s15
	v_cvt_f32_i32_e32 v0, s8
	s_xor_b32 s21, s8, s9
	v_rcp_iflag_f32_e32 v2, v1
	s_ashr_i32 s21, s21, 30
	s_or_b32 s21, s21, 1
	v_and_b32_e32 v102, 31, v103
	v_mul_f32_e32 v2, v0, v2
	v_trunc_f32_e32 v2, v2
	v_fma_f32 v0, -v2, v1, v0
	v_cvt_i32_f32_e32 v2, v2
	v_cmp_ge_f32_e64 s[8:9], |v0|, |v1|
	s_and_b64 s[8:9], s[8:9], exec
	s_cselect_b32 s8, s21, 0
	v_readfirstlane_b32 s9, v2
	s_add_i32 s8, s9, s8
	s_sext_i32_i16 s9, s8
	s_mul_i32 s8, s8, s7
	s_sub_i32 s7, s15, s8
	s_sext_i32_i16 s7, s7
	s_lshl_b32 s41, s7, 5
	v_or_b32_e32 v104, s41, v102
	s_add_i32 s42, s6, s9
	v_lshlrev_b32_e32 v98, s40, v104
	v_bfe_u32 v105, v103, 5, 1
	v_add_u32_e32 v0, s42, v98
	v_mad_i64_i32 v[0:1], s[6:7], v0, s24, v[92:93]
	v_lshlrev_b32_e32 v94, 4, v105
	v_lshl_add_u64 v[4:5], v[0:1], 0, v[94:95]
	v_subrev_u32_e32 v10, 64, v104
	global_load_dwordx4 v[0:3], v[4:5], off offset:3072
	global_load_dwordx4 v[88:91], v[4:5], off offset:3104
	global_load_dwordx4 v[84:87], v[4:5], off offset:3136
	global_load_dwordx4 v[80:83], v[4:5], off offset:3168
	s_add_i32 s15, s20, -1
	v_max_i32_e32 v4, 0, v10
	v_min_u32_e32 v4, s15, v4
	v_lshlrev_b32_e32 v4, s40, v4
	v_add_u32_e32 v4, s42, v4
	v_mad_i64_i32 v[4:5], s[6:7], v4, s24, v[96:97]
	v_lshl_add_u64 v[4:5], v[4:5], 0, s[74:75]
	v_lshl_add_u64 v[4:5], v[4:5], 0, v[94:95]
	v_lshl_add_u64 v[8:9], v[4:5], 0, s[10:11]
	v_add_co_u32_e32 v4, vcc, s25, v4
	v_and_b32_e32 v99, 63, v103
	s_nop 0
	v_addc_co_u32_e32 v5, vcc, 0, v5, vcc
	global_load_dwordx4 v[4:7], v[4:5], off
	s_waitcnt vmcnt(0)
	v_mfma_f32_32x32x16_bf16 v[64:79], v[4:7], v[0:3], 0
	global_load_dwordx4 v[4:7], v[8:9], off offset:32
	s_waitcnt vmcnt(0)
	v_mfma_f32_32x32x16_bf16 v[64:79], v[4:7], v[88:91], v[64:79]
	global_load_dwordx4 v[4:7], v[8:9], off offset:64
	s_waitcnt vmcnt(0)
	v_mfma_f32_32x32x16_bf16 v[64:79], v[4:7], v[84:87], v[64:79]
	global_load_dwordx4 v[4:7], v[8:9], off offset:96
	s_waitcnt vmcnt(0)
	v_mfma_f32_32x32x16_bf16 v[64:79], v[4:7], v[80:83], v[64:79]
	v_max_i32_e32 v4, 0xffffffe0, v10
	v_add_u32_e32 v4, 32, v4
	v_min_u32_e32 v4, s15, v4
	v_lshlrev_b32_e32 v4, s40, v4
	v_add_u32_e32 v4, s42, v4
	v_mad_i64_i32 v[4:5], s[6:7], v4, s24, v[96:97]
	v_lshl_add_u64 v[4:5], v[4:5], 0, s[74:75]
	v_lshl_add_u64 v[4:5], v[4:5], 0, v[94:95]
	v_lshl_add_u64 v[8:9], v[4:5], 0, s[10:11]
	v_add_co_u32_e32 v4, vcc, s25, v4
	s_nop 1
	v_mul_f32_e32 v64, 0x3e38aa3b, v64
	v_addc_co_u32_e32 v5, vcc, 0, v5, vcc
	global_load_dwordx4 v[4:7], v[4:5], off
	v_mul_f32_e32 v65, 0x3e38aa3b, v65
	v_mul_f32_e32 v66, 0x3e38aa3b, v66
	v_mul_f32_e32 v67, 0x3e38aa3b, v67
	s_waitcnt vmcnt(0)
	v_mfma_f32_32x32x16_bf16 v[48:63], v[4:7], v[0:3], 0
	global_load_dwordx4 v[4:7], v[8:9], off offset:32
	s_waitcnt vmcnt(0)
	v_mfma_f32_32x32x16_bf16 v[48:63], v[4:7], v[88:91], v[48:63]
	global_load_dwordx4 v[4:7], v[8:9], off offset:64
	s_waitcnt vmcnt(0)
	v_mfma_f32_32x32x16_bf16 v[48:63], v[4:7], v[84:87], v[48:63]
	global_load_dwordx4 v[4:7], v[8:9], off offset:96
	s_waitcnt vmcnt(0)
	v_mfma_f32_32x32x16_bf16 v[48:63], v[4:7], v[80:83], v[48:63]
	v_max_i32_e32 v4, 0xffffffc0, v10
	v_add_u32_e32 v4, 64, v4
	v_min_u32_e32 v4, s15, v4
	v_lshlrev_b32_e32 v4, s40, v4
	v_add_u32_e32 v4, s42, v4
	v_mad_i64_i32 v[4:5], s[6:7], v4, s24, v[96:97]
	v_lshl_add_u64 v[4:5], v[4:5], 0, s[74:75]
	v_lshl_add_u64 v[4:5], v[4:5], 0, v[94:95]
	v_lshl_add_u64 v[8:9], v[4:5], 0, s[10:11]
	v_add_co_u32_e32 v4, vcc, s25, v4
	s_nop 1
	v_mul_f32_e32 v48, 0x3e38aa3b, v48
	v_addc_co_u32_e32 v5, vcc, 0, v5, vcc
	global_load_dwordx4 v[4:7], v[4:5], off
	v_mul_f32_e32 v49, 0x3e38aa3b, v49
	v_mul_f32_e32 v50, 0x3e38aa3b, v50
	s_waitcnt vmcnt(0)
	v_mfma_f32_32x32x16_bf16 v[32:47], v[4:7], v[0:3], 0
	global_load_dwordx4 v[4:7], v[8:9], off offset:32
	s_waitcnt vmcnt(0)
	v_mfma_f32_32x32x16_bf16 v[32:47], v[4:7], v[88:91], v[32:47]
	global_load_dwordx4 v[4:7], v[8:9], off offset:64
	s_waitcnt vmcnt(0)
	v_mfma_f32_32x32x16_bf16 v[32:47], v[4:7], v[84:87], v[32:47]
	global_load_dwordx4 v[4:7], v[8:9], off offset:96
	s_waitcnt vmcnt(0)
	v_mfma_f32_32x32x16_bf16 v[32:47], v[4:7], v[80:83], v[32:47]
	v_max_i32_e32 v4, 0xffffffa0, v10
	v_add_u32_e32 v4, 0x60, v4
	v_min_u32_e32 v4, s15, v4
	v_lshlrev_b32_e32 v4, s40, v4
	v_add_u32_e32 v4, s42, v4
	v_mad_i64_i32 v[4:5], s[6:7], v4, s24, v[96:97]
	v_lshl_add_u64 v[4:5], v[4:5], 0, s[74:75]
	v_lshl_add_u64 v[4:5], v[4:5], 0, v[94:95]
	v_lshl_add_u64 v[8:9], v[4:5], 0, s[10:11]
	v_add_co_u32_e32 v4, vcc, s25, v4
	s_nop 1
	v_mul_f32_e32 v32, 0x3e38aa3b, v32
	v_addc_co_u32_e32 v5, vcc, 0, v5, vcc
	global_load_dwordx4 v[4:7], v[4:5], off
	v_mul_f32_e32 v33, 0x3e38aa3b, v33
	v_mul_f32_e32 v34, 0x3e38aa3b, v34
	s_waitcnt vmcnt(0)
	v_mfma_f32_32x32x16_bf16 v[16:31], v[4:7], v[0:3], 0
	global_load_dwordx4 v[4:7], v[8:9], off offset:32
	s_waitcnt vmcnt(0)
	v_mfma_f32_32x32x16_bf16 v[16:31], v[4:7], v[88:91], v[16:31]
	global_load_dwordx4 v[4:7], v[8:9], off offset:64
	s_waitcnt vmcnt(0)
	v_mfma_f32_32x32x16_bf16 v[16:31], v[4:7], v[84:87], v[16:31]
	global_load_dwordx4 v[4:7], v[8:9], off offset:96
	s_waitcnt vmcnt(0)
; __device__ __forceinline__ int crow(int r, int hi) { return (r & 3) + 8 * (r >> 2) + 4 * hi; }
; __device__ __forceinline__ void dil_wave_item(const bf16* __restrict__ qkv, bf16* __restrict__ odil, float* __restrict__ lse,
;                               int pat, int g  , int head, char* wl  , const int W) {
;     ...
;     for (int d0 = 0; d0 < 4; ++d0) {
;       bf16x8 kf = *reinterpret_cast<const bf16x8*>(kp + d0 * 16);
;       a = __builtin_amdgcn_mfma_f32_32x32x16_bf16(kf, qr[d0], a, 0, 0, 0);
;     }
;     sc[kb] = a;
;   }
;   float mx = -1e30f;
; #pragma unroll
;   for (int kb = 0; kb < 5; ++kb)
; #pragma unroll
;     for (int r = 0; r < 16; ++r) {
;       const int rel = kb * 32 - 64 + crow(r, hi) - r32;
;       const int kc = i0 + r32 + rel;
;       const bool ok = (rel >= -64) && (rel <= 64) && (kc >= 0) && (kc < L);
;       const float s = ok ? sc[kb][r] * AC : -1e30f;
;       sc[kb][r] = s; mx = fmaxf(mx, s);
;     }
	v_mfma_f32_32x32x16_bf16 v[16:31], v[4:7], v[80:83], v[16:31]
	v_max_i32_e32 v4, 0xffffff80, v10
	v_add_u32_e32 v4, 0x80, v4
	v_min_u32_e32 v4, s15, v4
	v_lshlrev_b32_e32 v4, s40, v4
	v_add_u32_e32 v4, s42, v4
	v_mad_i64_i32 v[4:5], s[6:7], v4, s24, v[96:97]
	v_lshl_add_u64 v[4:5], v[4:5], 0, s[74:75]
	v_lshl_add_u64 v[4:5], v[4:5], 0, v[94:95]
	v_lshl_add_u64 v[110:111], v[4:5], 0, s[10:11]
	v_add_co_u32_e32 v4, vcc, s25, v4
	global_load_dwordx4 v[106:109], v[110:111], off offset:32
	s_nop 0
	v_addc_co_u32_e32 v5, vcc, 0, v5, vcc
	global_load_dwordx4 v[4:7], v[4:5], off
	v_mul_f32_e32 v16, 0x3e38aa3b, v16
	s_waitcnt vmcnt(0)
	v_mfma_f32_32x32x16_bf16 v[0:15], v[4:7], v[0:3], 0
	v_mfma_f32_32x32x16_bf16 v[0:15], v[106:109], v[88:91], v[0:15]
	global_load_dwordx4 v[88:91], v[110:111], off offset:64
	s_waitcnt vmcnt(0)
	v_mfma_f32_32x32x16_bf16 v[0:15], v[88:91], v[84:87], v[0:15]
	global_load_dwordx4 v[84:87], v[110:111], off offset:96
	s_waitcnt vmcnt(0)
	v_mfma_f32_32x32x16_bf16 v[0:15], v[84:87], v[80:83], v[0:15]
	v_lshlrev_b32_e32 v80, 2, v105
	v_sub_u32_e32 v81, v80, v102
	v_add_u32_e32 v82, v104, v81
	v_subrev_u32_e32 v83, 64, v82
	v_cmp_gt_u32_e32 vcc, s26, v81
	v_cmp_gt_u32_e64 s[6:7], s20, v83
	s_and_b64 vcc, vcc, s[6:7]
	v_subrev_u32_e32 v83, 63, v82
	v_add_u32_e32 v86, 1, v81
	v_cndmask_b32_e32 v64, v101, v64, vcc
	v_cmp_gt_u32_e32 vcc, s26, v86
	v_cmp_gt_u32_e64 s[6:7], s20, v83
	s_and_b64 vcc, vcc, s[6:7]
	v_cndmask_b32_e32 v65, v101, v65, vcc
	s_mov_b32 s6, 0xf149f2ca
	v_subrev_u32_e32 v83, 62, v82
	v_add_u32_e32 v87, 2, v81
	v_max3_f32 v84, v64, s6, v65
	v_cmp_gt_u32_e32 vcc, s26, v87
	v_cmp_gt_u32_e64 s[6:7], s20, v83
	s_and_b64 vcc, vcc, s[6:7]
	v_subrev_u32_e32 v83, 61, v82
	v_add_u32_e32 v88, 3, v81
	v_cndmask_b32_e32 v66, v101, v66, vcc
	v_cmp_gt_u32_e32 vcc, s26, v88
	v_cmp_gt_u32_e64 s[6:7], s20, v83
	s_and_b64 vcc, vcc, s[6:7]
	v_cndmask_b32_e32 v83, v101, v67, vcc
	v_subrev_u32_e32 v67, 56, v82
	v_add_u32_e32 v89, 8, v81
	v_cmp_gt_u32_e32 vcc, s26, v89
	v_cmp_gt_u32_e64 s[6:7], s20, v67
	s_and_b64 vcc, vcc, s[6:7]
	v_mul_f32_e32 v67, 0x3e38aa3b, v68
	v_subrev_u32_e32 v68, 55, v82
	v_add_u32_e32 v90, 9, v81
	v_cndmask_b32_e32 v67, v101, v67, vcc
	v_cmp_gt_u32_e32 vcc, s26, v90
	v_cmp_gt_u32_e64 s[6:7], s20, v68
	s_and_b64 vcc, vcc, s[6:7]
	v_mul_f32_e32 v68, 0x3e38aa3b, v69
	v_subrev_u32_e32 v69, 54, v82
	v_add_u32_e32 v91, 10, v81
	v_cndmask_b32_e32 v68, v101, v68, vcc
	v_cmp_gt_u32_e32 vcc, s26, v91
	v_cmp_gt_u32_e64 s[6:7], s20, v69
	s_and_b64 vcc, vcc, s[6:7]
	v_mul_f32_e32 v69, 0x3e38aa3b, v70
	v_subrev_u32_e32 v70, 53, v82
	v_add_u32_e32 v105, 11, v81
	v_cndmask_b32_e32 v69, v101, v69, vcc
	v_cmp_gt_u32_e32 vcc, s26, v105
	v_cmp_gt_u32_e64 s[6:7], s20, v70
	s_and_b64 vcc, vcc, s[6:7]
	v_mul_f32_e32 v70, 0x3e38aa3b, v71
	v_cndmask_b32_e32 v71, v101, v70, vcc
	v_subrev_u32_e32 v70, 48, v82
	v_add_u32_e32 v106, 16, v81
	v_cmp_gt_u32_e32 vcc, s26, v106
	v_cmp_gt_u32_e64 s[6:7], s20, v70
	s_and_b64 vcc, vcc, s[6:7]
	v_mul_f32_e32 v70, 0x3e38aa3b, v72
	v_subrev_u32_e32 v72, 47, v82
	v_add_u32_e32 v107, 17, v81
	v_cndmask_b32_e32 v70, v101, v70, vcc
	v_cmp_gt_u32_e32 vcc, s26, v107
	v_cmp_gt_u32_e64 s[6:7], s20, v72
	s_and_b64 vcc, vcc, s[6:7]
	v_mul_f32_e32 v72, 0x3e38aa3b, v73
	v_subrev_u32_e32 v73, 46, v82
	v_add_u32_e32 v108, 18, v81
	v_cndmask_b32_e32 v72, v101, v72, vcc
	v_cmp_gt_u32_e32 vcc, s26, v108
	v_cmp_gt_u32_e64 s[6:7], s20, v73
	s_and_b64 vcc, vcc, s[6:7]
	v_mul_f32_e32 v73, 0x3e38aa3b, v74
	v_subrev_u32_e32 v74, 45, v82
	v_add_u32_e32 v109, 19, v81
	v_cndmask_b32_e32 v73, v101, v73, vcc
	v_cmp_gt_u32_e32 vcc, s26, v109
	v_cmp_gt_u32_e64 s[6:7], s20, v74
	s_and_b64 vcc, vcc, s[6:7]
	v_mul_f32_e32 v74, 0x3e38aa3b, v75
	v_cndmask_b32_e32 v75, v101, v74, vcc
	v_subrev_u32_e32 v74, 40, v82
	v_add_u32_e32 v110, 24, v81
	v_cmp_gt_u32_e32 vcc, s26, v110
	v_cmp_gt_u32_e64 s[6:7], s20, v74
	s_and_b64 vcc, vcc, s[6:7]
	v_mul_f32_e32 v74, 0x3e38aa3b, v76
	v_subrev_u32_e32 v76, 39, v82
	v_add_u32_e32 v111, 25, v81
	v_cndmask_b32_e32 v74, v101, v74, vcc
	v_cmp_gt_u32_e32 vcc, s26, v111
	v_cmp_gt_u32_e64 s[6:7], s20, v76
	v_max3_f32 v84, v84, v66, v83
	s_and_b64 vcc, vcc, s[6:7]
	v_mul_f32_e32 v76, 0x3e38aa3b, v77
	v_subrev_u32_e32 v77, 38, v82
	v_add_u32_e32 v112, 26, v81
	v_max3_f32 v84, v84, v67, v68
	v_cndmask_b32_e32 v76, v101, v76, vcc
	v_cmp_gt_u32_e32 vcc, s26, v112
	v_cmp_gt_u32_e64 s[6:7], s20, v77
	v_max3_f32 v84, v84, v69, v71
	s_and_b64 vcc, vcc, s[6:7]
	v_mul_f32_e32 v77, 0x3e38aa3b, v78
	v_subrev_u32_e32 v78, 37, v82
	v_add_u32_e32 v113, 27, v81
	v_max3_f32 v84, v84, v70, v72
	v_cndmask_b32_e32 v77, v101, v77, vcc
	v_cmp_gt_u32_e32 vcc, s26, v113
	v_cmp_gt_u32_e64 s[6:7], s20, v78
	v_max3_f32 v84, v84, v73, v75
	s_and_b64 vcc, vcc, s[6:7]
	v_mul_f32_e32 v78, 0x3e38aa3b, v79
	v_max3_f32 v84, v84, v74, v76
	v_cndmask_b32_e32 v78, v101, v78, vcc
	v_max3_f32 v79, v84, v77, v78
	v_subrev_u32_e32 v84, 32, v82
	v_cmp_gt_u32_e32 vcc, s20, v84
	v_subrev_u32_e32 v84, 31, v82
	v_mul_f32_e32 v0, 0x3e38aa3b, v0
	v_cndmask_b32_e32 v48, v101, v48, vcc
	v_cmp_gt_u32_e32 vcc, s20, v84
	v_mul_f32_e32 v1, 0x3e38aa3b, v1
	v_mul_f32_e32 v2, 0x3e38aa3b, v2
	v_cndmask_b32_e32 v49, v101, v49, vcc
	v_max3_f32 v85, v79, v48, v49
	v_subrev_u32_e32 v79, 30, v82
	v_cmp_gt_u32_e32 vcc, s20, v79
	v_mul_f32_e32 v3, 0x3e38aa3b, v3
	v_mul_f32_e32 v4, 0x3e38aa3b, v4
	v_cndmask_b32_e32 v79, v101, v50, vcc
	v_subrev_u32_e32 v50, 29, v82
	v_cmp_gt_u32_e32 vcc, s20, v50
	v_mul_f32_e32 v50, 0x3e38aa3b, v51
	v_subrev_u32_e32 v51, 23, v82
	v_cndmask_b32_e32 v84, v101, v50, vcc
	v_subrev_u32_e32 v50, 24, v82
	v_cmp_gt_u32_e32 vcc, s20, v50
; __device__ __forceinline__ int crow(int r, int hi) { return (r & 3) + 8 * (r >> 2) + 4 * hi; }
; __device__ __forceinline__ void dil_wave_item(const bf16* __restrict__ qkv, bf16* __restrict__ odil, float* __restrict__ lse,
;                               int pat, int g  , int head, char* wl  , const int W) {
;     ...
; #pragma unroll
;   for (int kb = 0; kb < 5; ++kb)
; #pragma unroll
;     for (int r = 0; r < 16; ++r) {
;       const int rel = kb * 32 - 64 + crow(r, hi) - r32;
;       const int kc = i0 + r32 + rel;
;       const bool ok = (rel >= -64) && (rel <= 64) && (kc >= 0) && (kc < L);
;       const float s = ok ? sc[kb][r] * AC : -1e30f;
;       sc[kb][r] = s; mx = fmaxf(mx, s);
;     }
	v_mul_f32_e32 v50, 0x3e38aa3b, v52
	v_max3_f32 v85, v85, v79, v84
	v_cndmask_b32_e32 v50, v101, v50, vcc
	v_cmp_gt_u32_e32 vcc, s20, v51
	v_mul_f32_e32 v51, 0x3e38aa3b, v53
	v_subrev_u32_e32 v53, 22, v82
	v_cndmask_b32_e32 v51, v101, v51, vcc
	v_cmp_gt_u32_e32 vcc, s20, v53
	v_mul_f32_e32 v53, 0x3e38aa3b, v54
	v_subrev_u32_e32 v54, 21, v82
	v_cndmask_b32_e32 v53, v101, v53, vcc
	v_cmp_gt_u32_e32 vcc, s20, v54
	v_mul_f32_e32 v54, 0x3e38aa3b, v55
	v_max3_f32 v52, v85, v50, v51
	v_cndmask_b32_e32 v85, v101, v54, vcc
	v_max3_f32 v55, v52, v53, v85
	v_add_u32_e32 v52, -16, v82
	v_cmp_gt_u32_e32 vcc, s20, v52
	v_mul_f32_e32 v52, 0x3e38aa3b, v56
	v_add_u32_e32 v54, -15, v82
	v_cndmask_b32_e32 v52, v101, v52, vcc
	v_cmp_gt_u32_e32 vcc, s20, v54
	v_mul_f32_e32 v54, 0x3e38aa3b, v57
	v_add_u32_e32 v56, -14, v82
	v_cndmask_b32_e32 v54, v101, v54, vcc
	v_cmp_gt_u32_e32 vcc, s20, v56
	v_mul_f32_e32 v56, 0x3e38aa3b, v58
	v_add_u32_e32 v58, -7, v82
	v_cndmask_b32_e32 v57, v101, v56, vcc
	v_add_u32_e32 v56, -13, v82
	v_cmp_gt_u32_e32 vcc, s20, v56
	v_mul_f32_e32 v56, 0x3e38aa3b, v59
	v_max3_f32 v55, v55, v52, v54
	v_cndmask_b32_e32 v59, v101, v56, vcc
	v_add_u32_e32 v56, -8, v82
	v_cmp_gt_u32_e32 vcc, s20, v56
	v_mul_f32_e32 v56, 0x3e38aa3b, v60
	v_add_u32_e32 v60, -6, v82
	v_cndmask_b32_e32 v56, v101, v56, vcc
	v_cmp_gt_u32_e32 vcc, s20, v58
	v_mul_f32_e32 v58, 0x3e38aa3b, v61
	v_add_u32_e32 v61, -5, v82
	v_cndmask_b32_e32 v58, v101, v58, vcc
	v_cmp_gt_u32_e32 vcc, s20, v60
	v_mul_f32_e32 v60, 0x3e38aa3b, v62
	v_add_u32_e32 v62, v104, v86
	v_cndmask_b32_e32 v60, v101, v60, vcc
	v_cmp_gt_u32_e32 vcc, s20, v61
	v_mul_f32_e32 v61, 0x3e38aa3b, v63
	v_max3_f32 v55, v55, v57, v59
	v_cndmask_b32_e32 v61, v101, v61, vcc
	v_cmp_gt_u32_e32 vcc, s20, v82
	v_max3_f32 v55, v55, v56, v58
	v_max3_f32 v55, v55, v60, v61
	v_cndmask_b32_e32 v32, v101, v32, vcc
	v_cmp_gt_u32_e32 vcc, s20, v62
	v_add_u32_e32 v62, v104, v87
	v_mul_f32_e32 v5, 0x3e38aa3b, v5
	v_cndmask_b32_e32 v33, v101, v33, vcc
	v_cmp_gt_u32_e32 vcc, s20, v62
	v_max3_f32 v55, v55, v32, v33
	v_mul_f32_e32 v6, 0x3e38aa3b, v6
	v_cndmask_b32_e32 v62, v101, v34, vcc
	v_add_u32_e32 v34, v104, v88
	v_cmp_gt_u32_e32 vcc, s20, v34
	v_mul_f32_e32 v34, 0x3e38aa3b, v35
	v_add_u32_e32 v35, v104, v89
	v_cndmask_b32_e32 v63, v101, v34, vcc
	v_cmp_gt_u32_e32 vcc, s20, v35
	v_mul_f32_e32 v35, 0x3e38aa3b, v36
	v_add_u32_e32 v36, v104, v90
	v_cndmask_b32_e32 v35, v101, v35, vcc
	v_cmp_gt_u32_e32 vcc, s20, v36
	v_mul_f32_e32 v36, 0x3e38aa3b, v37
	v_add_u32_e32 v37, v104, v91
	v_cndmask_b32_e32 v36, v101, v36, vcc
	v_cmp_gt_u32_e32 vcc, s20, v37
	v_mul_f32_e32 v37, 0x3e38aa3b, v38
	v_max3_f32 v34, v55, v62, v63
	v_cndmask_b32_e32 v88, v101, v37, vcc
	v_add_u32_e32 v37, v104, v105
	v_cmp_gt_u32_e32 vcc, s20, v37
	v_mul_f32_e32 v37, 0x3e38aa3b, v39
	v_max3_f32 v34, v34, v35, v36
	v_cndmask_b32_e32 v105, v101, v37, vcc
	v_add_u32_e32 v37, v104, v106
	v_cmp_gt_u32_e32 vcc, s20, v37
	v_mul_f32_e32 v37, 0x3e38aa3b, v40
	v_max3_f32 v34, v34, v88, v105
	v_cndmask_b32_e32 v87, v101, v37, vcc
	v_add_u32_e32 v37, v104, v107
	v_cmp_gt_u32_e32 vcc, s20, v37
	v_mul_f32_e32 v37, 0x3e38aa3b, v41
	v_mul_f32_e32 v7, 0x3e38aa3b, v7
	v_cndmask_b32_e32 v90, v101, v37, vcc
	v_add_u32_e32 v37, v104, v108
	v_cmp_gt_u32_e32 vcc, s20, v37
	v_mul_f32_e32 v37, 0x3e38aa3b, v42
	v_max3_f32 v34, v34, v87, v90
	v_cndmask_b32_e32 v108, v101, v37, vcc
	v_add_u32_e32 v37, v104, v109
	v_cmp_gt_u32_e32 vcc, s20, v37
	v_mul_f32_e32 v37, 0x3e38aa3b, v43
	v_mul_f32_e32 v8, 0x3e38aa3b, v8
	v_cndmask_b32_e32 v109, v101, v37, vcc
	v_add_u32_e32 v37, v104, v110
	v_cmp_gt_u32_e32 vcc, s20, v37
	v_mul_f32_e32 v37, 0x3e38aa3b, v44
	v_max3_f32 v34, v34, v108, v109
	v_cndmask_b32_e32 v107, v101, v37, vcc
	v_add_u32_e32 v37, v104, v111
	v_cmp_gt_u32_e32 vcc, s20, v37
	v_mul_f32_e32 v37, 0x3e38aa3b, v45
	v_mul_f32_e32 v9, 0x3e38aa3b, v9
	v_cndmask_b32_e32 v45, v101, v37, vcc
	v_add_u32_e32 v37, v104, v112
	v_cmp_gt_u32_e32 vcc, s20, v37
	v_mul_f32_e32 v37, 0x3e38aa3b, v46
	v_max3_f32 v34, v34, v107, v45
	v_cndmask_b32_e32 v110, v101, v37, vcc
	v_add_u32_e32 v37, v104, v113
	v_cmp_gt_u32_e32 vcc, s20, v37
	v_mul_f32_e32 v37, 0x3e38aa3b, v47
	v_mul_f32_e32 v10, 0x3e38aa3b, v10
	v_cndmask_b32_e32 v111, v101, v37, vcc
	v_add_u32_e32 v37, 32, v82
	v_cmp_gt_u32_e32 vcc, s20, v37
	v_max3_f32 v34, v34, v110, v111
	v_mul_f32_e32 v11, 0x3e38aa3b, v11
	v_cndmask_b32_e32 v46, v101, v16, vcc
	v_add_u32_e32 v16, 33, v82
	v_cmp_gt_u32_e32 vcc, s20, v16
	v_mul_f32_e32 v16, 0x3e38aa3b, v17
	v_add_u32_e32 v17, 34, v82
	v_cndmask_b32_e32 v104, v101, v16, vcc
	v_cmp_gt_u32_e32 vcc, s20, v17
	v_mul_f32_e32 v17, 0x3e38aa3b, v18
	v_add_u32_e32 v18, 0x80, v81
	v_cndmask_b32_e32 v113, v101, v17, vcc
	v_add_u32_e32 v17, 35, v82
	v_cmp_gt_u32_e32 vcc, s20, v17
	v_mul_f32_e32 v17, 0x3e38aa3b, v19
	v_max3_f32 v16, v34, v46, v104
	v_cndmask_b32_e32 v115, v101, v17, vcc
	v_add_u32_e32 v17, 40, v82
	v_cmp_gt_u32_e32 vcc, s20, v17
	v_mul_f32_e32 v17, 0x3e38aa3b, v20
	v_max3_f32 v16, v16, v113, v115
	v_cndmask_b32_e32 v112, v101, v17, vcc
	v_add_u32_e32 v17, 41, v82
	v_cmp_gt_u32_e32 vcc, s20, v17
	v_mul_f32_e32 v17, 0x3e38aa3b, v21
	v_mul_f32_e32 v12, 0x3e38aa3b, v12
	v_cndmask_b32_e32 v114, v101, v17, vcc
	v_add_u32_e32 v17, 42, v82
	v_cmp_gt_u32_e32 vcc, s20, v17
	v_mul_f32_e32 v17, 0x3e38aa3b, v22
	v_max3_f32 v16, v16, v112, v114
	v_cndmask_b32_e32 v117, v101, v17, vcc
	v_add_u32_e32 v17, 43, v82
	v_cmp_gt_u32_e32 vcc, s20, v17
	v_mul_f32_e32 v17, 0x3e38aa3b, v23
	v_mul_f32_e32 v13, 0x3e38aa3b, v13
	v_cndmask_b32_e32 v119, v101, v17, vcc
	v_add_u32_e32 v17, 48, v82
	v_cmp_gt_u32_e32 vcc, s20, v17
; __device__ __forceinline__ float shfl_idx(float v, int srclane) { return __int_as_float(__builtin_amdgcn_ds_bpermute(srclane << 2, __float_as_int(v))); }
; __device__ __forceinline__ int crow(int r, int hi) { return (r & 3) + 8 * (r >> 2) + 4 * hi; }
; __device__ __forceinline__ void dil_wave_item(const bf16* __restrict__ qkv, bf16* __restrict__ odil, float* __restrict__ lse,
;                               int pat, int g  , int head, char* wl  , const int W) {
;     ...
; #pragma unroll
;   for (int kb = 0; kb < 5; ++kb)
; #pragma unroll
;     for (int r = 0; r < 16; ++r) {
;       const int rel = kb * 32 - 64 + crow(r, hi) - r32;
;       const int kc = i0 + r32 + rel;
;       const bool ok = (rel >= -64) && (rel <= 64) && (kc >= 0) && (kc < L);
;       const float s = ok ? sc[kb][r] * AC : -1e30f;
;       sc[kb][r] = s; mx = fmaxf(mx, s);
;     }
;   mx = fmaxf(mx, shfl_idx(mx, lane ^ 32));
	v_mul_f32_e32 v17, 0x3e38aa3b, v24
	v_max3_f32 v16, v16, v117, v119
	v_cndmask_b32_e32 v116, v101, v17, vcc
	v_add_u32_e32 v17, 49, v82
	v_cmp_gt_u32_e32 vcc, s20, v17
	v_mul_f32_e32 v17, 0x3e38aa3b, v25
	v_mul_f32_e32 v14, 0x3e38aa3b, v14
	v_cndmask_b32_e32 v118, v101, v17, vcc
	v_add_u32_e32 v17, 50, v82
	v_cmp_gt_u32_e32 vcc, s20, v17
	v_mul_f32_e32 v17, 0x3e38aa3b, v26
	v_max3_f32 v16, v16, v116, v118
	v_cndmask_b32_e32 v121, v101, v17, vcc
	v_add_u32_e32 v17, 51, v82
	v_cmp_gt_u32_e32 vcc, s20, v17
	v_mul_f32_e32 v17, 0x3e38aa3b, v27
	v_mul_f32_e32 v15, 0x3e38aa3b, v15
	v_cndmask_b32_e32 v123, v101, v17, vcc
	v_add_u32_e32 v17, 56, v82
	v_cmp_gt_u32_e32 vcc, s20, v17
	v_mul_f32_e32 v17, 0x3e38aa3b, v28
	v_max3_f32 v16, v16, v121, v123
	v_cndmask_b32_e32 v120, v101, v17, vcc
	v_add_u32_e32 v17, 57, v82
	v_cmp_gt_u32_e32 vcc, s20, v17
	v_mul_f32_e32 v17, 0x3e38aa3b, v29
	s_nop 0
	v_cndmask_b32_e32 v122, v101, v17, vcc
	v_add_u32_e32 v17, 58, v82
	v_cmp_gt_u32_e32 vcc, s20, v17
	v_mul_f32_e32 v17, 0x3e38aa3b, v30
	v_max3_f32 v16, v16, v120, v122
	v_cndmask_b32_e32 v124, v101, v17, vcc
	v_add_u32_e32 v17, 59, v82
	v_cmp_gt_u32_e32 vcc, s20, v17
	v_mul_f32_e32 v17, 0x3e38aa3b, v31
	s_nop 0
	v_cndmask_b32_e32 v125, v101, v17, vcc
	v_add_u32_e32 v17, 64, v82
	v_cmp_gt_u32_e32 vcc, s26, v18
	v_cmp_gt_u32_e64 s[6:7], s20, v17
	s_and_b64 vcc, vcc, s[6:7]
	v_add_u32_e32 v17, 0x41, v82
	s_movk_i32 s6, 0xff7e
	v_cndmask_b32_e32 v0, v101, v0, vcc
	v_cmp_lt_u32_e32 vcc, s6, v81
	v_cmp_gt_u32_e64 s[6:7], s20, v17
	s_and_b64 vcc, vcc, s[6:7]
	v_add_u32_e32 v17, 0x42, v82
	v_add_u32_e32 v18, 0x82, v81
	v_cndmask_b32_e32 v1, v101, v1, vcc
	v_cmp_gt_u32_e32 vcc, s26, v18
	v_cmp_gt_u32_e64 s[6:7], s20, v17
	s_and_b64 vcc, vcc, s[6:7]
	v_add_u32_e32 v17, 0x43, v82
	v_add_u32_e32 v18, 0x83, v81
	v_cndmask_b32_e32 v2, v101, v2, vcc
	v_cmp_gt_u32_e32 vcc, s26, v18
	v_cmp_gt_u32_e64 s[6:7], s20, v17
	s_and_b64 vcc, vcc, s[6:7]
	v_add_u32_e32 v17, 0x48, v82
	v_add_u32_e32 v18, 0x88, v81
	v_cndmask_b32_e32 v3, v101, v3, vcc
	v_cmp_gt_u32_e32 vcc, s26, v18
	v_cmp_gt_u32_e64 s[6:7], s20, v17
	s_and_b64 vcc, vcc, s[6:7]
	v_add_u32_e32 v17, 0x49, v82
	v_add_u32_e32 v18, 0x89, v81
	v_cndmask_b32_e32 v4, v101, v4, vcc
	v_cmp_gt_u32_e32 vcc, s26, v18
	v_cmp_gt_u32_e64 s[6:7], s20, v17
	s_and_b64 vcc, vcc, s[6:7]
	v_add_u32_e32 v17, 0x4a, v82
	v_add_u32_e32 v18, 0x8a, v81
	v_cndmask_b32_e32 v5, v101, v5, vcc
	v_cmp_gt_u32_e32 vcc, s26, v18
	v_cmp_gt_u32_e64 s[6:7], s20, v17
	s_and_b64 vcc, vcc, s[6:7]
	v_add_u32_e32 v17, 0x4b, v82
	v_add_u32_e32 v18, 0x8b, v81
	v_cndmask_b32_e32 v6, v101, v6, vcc
	v_cmp_gt_u32_e32 vcc, s26, v18
	v_cmp_gt_u32_e64 s[6:7], s20, v17
	s_and_b64 vcc, vcc, s[6:7]
	v_add_u32_e32 v17, 0x50, v82
	v_add_u32_e32 v18, 0x90, v81
	v_cndmask_b32_e32 v7, v101, v7, vcc
	v_cmp_gt_u32_e32 vcc, s26, v18
	v_cmp_gt_u32_e64 s[6:7], s20, v17
	s_and_b64 vcc, vcc, s[6:7]
	v_add_u32_e32 v17, 0x51, v82
	v_add_u32_e32 v18, 0x91, v81
	v_cndmask_b32_e32 v8, v101, v8, vcc
	v_cmp_gt_u32_e32 vcc, s26, v18
	v_cmp_gt_u32_e64 s[6:7], s20, v17
	s_and_b64 vcc, vcc, s[6:7]
	v_add_u32_e32 v17, 0x52, v82
	v_add_u32_e32 v18, 0x92, v81
	v_cndmask_b32_e32 v9, v101, v9, vcc
	v_cmp_gt_u32_e32 vcc, s26, v18
	v_cmp_gt_u32_e64 s[6:7], s20, v17
	s_and_b64 vcc, vcc, s[6:7]
	v_add_u32_e32 v17, 0x53, v82
	v_add_u32_e32 v18, 0x93, v81
	v_cndmask_b32_e32 v10, v101, v10, vcc
	v_cmp_gt_u32_e32 vcc, s26, v18
	v_cmp_gt_u32_e64 s[6:7], s20, v17
	s_and_b64 vcc, vcc, s[6:7]
	v_add_u32_e32 v17, 0x58, v82
	v_add_u32_e32 v18, 0x98, v81
	v_cndmask_b32_e32 v11, v101, v11, vcc
	v_cmp_gt_u32_e32 vcc, s26, v18
	v_cmp_gt_u32_e64 s[6:7], s20, v17
	v_max3_f32 v16, v16, v124, v125
	s_and_b64 vcc, vcc, s[6:7]
	v_add_u32_e32 v17, 0x59, v82
	v_add_u32_e32 v18, 0x99, v81
	v_max3_f32 v16, v16, v0, v1
	v_cndmask_b32_e32 v12, v101, v12, vcc
	v_cmp_gt_u32_e32 vcc, s26, v18
	v_cmp_gt_u32_e64 s[6:7], s20, v17
	v_max3_f32 v16, v16, v2, v3
	s_and_b64 vcc, vcc, s[6:7]
	v_add_u32_e32 v17, 0x5a, v82
	v_add_u32_e32 v18, 0x9a, v81
	v_max3_f32 v16, v16, v4, v5
	v_cndmask_b32_e32 v13, v101, v13, vcc
	v_cmp_gt_u32_e32 vcc, s26, v18
	v_cmp_gt_u32_e64 s[6:7], s20, v17
	v_max3_f32 v16, v16, v6, v7
	s_and_b64 vcc, vcc, s[6:7]
	v_add_u32_e32 v17, 0x5b, v82
	v_add_u32_e32 v18, 0x9b, v81
	v_max3_f32 v16, v16, v8, v9
	v_cndmask_b32_e32 v14, v101, v14, vcc
	v_cmp_gt_u32_e32 vcc, s26, v18
	v_cmp_gt_u32_e64 s[6:7], s20, v17
	v_max3_f32 v16, v16, v10, v11
	s_and_b64 vcc, vcc, s[6:7]
	v_max3_f32 v16, v16, v12, v13
	v_cndmask_b32_e32 v15, v101, v15, vcc
	v_lshlrev_b32_e32 v17, 2, v99
	v_max3_f32 v16, v16, v14, v15
	v_xor_b32_e32 v126, 0x80, v17
	ds_bpermute_b32 v17, v126, v16
	s_waitcnt lgkmcnt(0)
; __device__ __forceinline__ float shfl_idx(float v, int srclane) { return __int_as_float(__builtin_amdgcn_ds_bpermute(srclane << 2, __float_as_int(v))); }
; __device__ __forceinline__ void dil_wave_item(const bf16* __restrict__ qkv, bf16* __restrict__ odil, float* __restrict__ lse,
;                               int pat, int g  , int head, char* wl  , const int W) {
;     ...
;   float ls = 0.f;
; #pragma unroll
;   for (int kb = 0; kb < 5; ++kb)
; #pragma unroll
;     for (int r = 0; r < 16; ++r) { const float e = __builtin_amdgcn_exp2f(sc[kb][r] - mx); sc[kb][r] = e; ls += e; }
;   ls += shfl_idx(ls, lane ^ 32);
	v_max_f32_e32 v17, v17, v17
	v_max_f32_e32 v34, v16, v17
	v_sub_f32_e32 v16, v64, v34
	v_exp_f32_e32 v16, v16
	v_sub_f32_e32 v17, v65, v34
	v_exp_f32_e32 v17, v17
	v_sub_f32_e32 v41, v84, v34
	v_add_f32_e32 v18, 0, v16
	v_exp_f32_e32 v41, v41
	v_add_f32_e32 v19, v17, v18
	v_sub_f32_e32 v18, v66, v34
	v_exp_f32_e32 v18, v18
	v_sub_f32_e32 v42, v50, v34
	v_exp_f32_e32 v44, v42
	v_sub_f32_e32 v42, v51, v34
	v_add_f32_e32 v20, v18, v19
	v_sub_f32_e32 v19, v83, v34
	v_exp_f32_e32 v19, v19
	v_exp_f32_e32 v50, v42
	v_sub_f32_e32 v42, v53, v34
	v_exp_f32_e32 v55, v42
	v_add_f32_e32 v21, v19, v20
	v_sub_f32_e32 v20, v67, v34
	v_exp_f32_e32 v20, v20
	v_sub_f32_e32 v42, v85, v34
	v_exp_f32_e32 v65, v42
	v_sub_f32_e32 v42, v52, v34
	v_add_f32_e32 v22, v20, v21
	v_sub_f32_e32 v21, v68, v34
	v_exp_f32_e32 v21, v21
	v_exp_f32_e32 v68, v42
	v_sub_f32_e32 v42, v54, v34
	v_sub_f32_e32 v32, v32, v34
	v_add_f32_e32 v23, v21, v22
	v_sub_f32_e32 v22, v69, v34
	v_exp_f32_e32 v22, v22
	v_sub_f32_e32 v33, v33, v34
	v_sub_f32_e32 v0, v0, v34
	v_sub_f32_e32 v1, v1, v34
	v_add_f32_e32 v24, v22, v23
	v_sub_f32_e32 v23, v71, v34
	v_exp_f32_e32 v23, v23
	s_nop 0
	v_add_f32_e32 v25, v23, v24
	v_sub_f32_e32 v24, v70, v34
	v_exp_f32_e32 v24, v24
	s_nop 0
	v_add_f32_e32 v26, v24, v25
	v_sub_f32_e32 v25, v72, v34
	v_exp_f32_e32 v25, v25
	s_nop 0
	v_add_f32_e32 v27, v25, v26
	v_sub_f32_e32 v26, v73, v34
	v_exp_f32_e32 v26, v26
	v_exp_f32_e32 v73, v42
	v_sub_f32_e32 v42, v57, v34
	v_add_f32_e32 v28, v26, v27
	v_sub_f32_e32 v27, v75, v34
	v_exp_f32_e32 v27, v27
	s_nop 0
	v_add_f32_e32 v29, v27, v28
	v_sub_f32_e32 v28, v74, v34
	v_exp_f32_e32 v28, v28
	s_nop 0
	v_add_f32_e32 v30, v28, v29
	v_sub_f32_e32 v29, v76, v34
	v_exp_f32_e32 v29, v29
	v_exp_f32_e32 v76, v42
	v_sub_f32_e32 v42, v59, v34
	v_exp_f32_e32 v81, v42
	v_add_f32_e32 v31, v29, v30
	v_sub_f32_e32 v30, v77, v34
	v_exp_f32_e32 v30, v30
	v_sub_f32_e32 v42, v56, v34
	v_exp_f32_e32 v86, v42
	v_sub_f32_e32 v42, v58, v34
	v_add_f32_e32 v37, v30, v31
	v_sub_f32_e32 v31, v78, v34
	v_exp_f32_e32 v31, v31
	v_exp_f32_e32 v89, v42
	v_sub_f32_e32 v42, v60, v34
	v_exp_f32_e32 v91, v42
	v_add_f32_e32 v38, v31, v37
	v_sub_f32_e32 v37, v48, v34
	v_exp_f32_e32 v37, v37
	v_sub_f32_e32 v42, v61, v34
	v_exp_f32_e32 v106, v42
	v_exp_f32_e32 v48, v1
	v_add_f32_e32 v39, v37, v38
	v_sub_f32_e32 v38, v49, v34
	v_exp_f32_e32 v38, v38
	v_sub_f32_e32 v1, v2, v34
	v_exp_f32_e32 v49, v1
	v_sub_f32_e32 v1, v3, v34
	v_add_f32_e32 v40, v38, v39
	v_sub_f32_e32 v39, v79, v34
	v_exp_f32_e32 v39, v39
	v_exp_f32_e32 v52, v1
	v_sub_f32_e32 v1, v4, v34
	v_exp_f32_e32 v53, v1
	v_add_f32_e32 v40, v39, v40
	v_add_f32_e32 v40, v41, v40
	v_add_f32_e32 v40, v44, v40
	v_add_f32_e32 v40, v50, v40
	v_add_f32_e32 v40, v55, v40
	v_add_f32_e32 v40, v65, v40
	v_add_f32_e32 v40, v68, v40
	v_add_f32_e32 v40, v73, v40
	v_add_f32_e32 v40, v76, v40
	v_add_f32_e32 v40, v81, v40
	v_add_f32_e32 v40, v86, v40
	v_add_f32_e32 v40, v89, v40
	v_add_f32_e32 v40, v91, v40
	v_add_f32_e32 v42, v106, v40
	v_exp_f32_e32 v40, v32
	v_sub_f32_e32 v1, v5, v34
	v_exp_f32_e32 v56, v1
	v_sub_f32_e32 v1, v6, v34
	v_add_f32_e32 v32, v40, v42
	v_exp_f32_e32 v42, v33
	v_sub_f32_e32 v33, v62, v34
	v_exp_f32_e32 v43, v33
	v_sub_f32_e32 v33, v63, v34
	v_exp_f32_e32 v47, v33
	v_sub_f32_e32 v33, v35, v34
	v_exp_f32_e32 v62, v33
	v_sub_f32_e32 v33, v36, v34
	v_add_f32_e32 v32, v42, v32
	v_exp_f32_e32 v70, v33
	v_sub_f32_e32 v33, v88, v34
	v_add_f32_e32 v32, v43, v32
	v_exp_f32_e32 v74, v33
	v_sub_f32_e32 v33, v105, v34
	v_add_f32_e32 v32, v47, v32
	v_exp_f32_e32 v77, v33
	v_sub_f32_e32 v33, v87, v34
	v_add_f32_e32 v32, v62, v32
	v_exp_f32_e32 v78, v33
	v_sub_f32_e32 v33, v90, v34
	v_add_f32_e32 v32, v70, v32
	v_exp_f32_e32 v82, v33
	v_sub_f32_e32 v33, v108, v34
	v_add_f32_e32 v32, v74, v32
	v_exp_f32_e32 v84, v33
	v_sub_f32_e32 v33, v109, v34
	v_add_f32_e32 v32, v77, v32
	v_exp_f32_e32 v88, v33
	v_sub_f32_e32 v33, v107, v34
	v_add_f32_e32 v32, v78, v32
	v_exp_f32_e32 v105, v33
	v_sub_f32_e32 v33, v45, v34
	v_add_f32_e32 v32, v82, v32
	v_exp_f32_e32 v108, v33
	v_sub_f32_e32 v33, v110, v34
	v_add_f32_e32 v32, v84, v32
	v_exp_f32_e32 v109, v33
	v_sub_f32_e32 v33, v111, v34
	v_add_f32_e32 v32, v88, v32
	v_exp_f32_e32 v111, v33
	v_sub_f32_e32 v33, v46, v34
	v_add_f32_e32 v32, v105, v32
	v_exp_f32_e32 v46, v33
	v_sub_f32_e32 v33, v104, v34
	v_add_f32_e32 v32, v108, v32
	v_exp_f32_e32 v51, v33
	v_sub_f32_e32 v33, v113, v34
	v_add_f32_e32 v32, v109, v32
	v_exp_f32_e32 v58, v33
	v_sub_f32_e32 v33, v115, v34
	v_add_f32_e32 v32, v111, v32
	v_exp_f32_e32 v67, v33
	v_sub_f32_e32 v33, v112, v34
	v_add_f32_e32 v32, v46, v32
	v_exp_f32_e32 v75, v33
	v_sub_f32_e32 v33, v114, v34
	v_add_f32_e32 v32, v51, v32
	v_exp_f32_e32 v79, v33
	v_sub_f32_e32 v33, v117, v34
	v_add_f32_e32 v32, v58, v32
	v_exp_f32_e32 v83, v33
	v_sub_f32_e32 v33, v119, v34
	v_add_f32_e32 v32, v67, v32
	v_exp_f32_e32 v85, v33
	v_sub_f32_e32 v33, v116, v34
	v_add_f32_e32 v32, v75, v32
	v_exp_f32_e32 v87, v33
	v_sub_f32_e32 v33, v118, v34
	v_add_f32_e32 v32, v79, v32
	v_exp_f32_e32 v90, v33
	v_sub_f32_e32 v33, v121, v34
	v_add_f32_e32 v32, v83, v32
	v_exp_f32_e32 v104, v33
	v_sub_f32_e32 v33, v123, v34
	v_add_f32_e32 v32, v85, v32
	v_exp_f32_e32 v107, v33
	v_sub_f32_e32 v33, v120, v34
	v_add_f32_e32 v32, v87, v32
	v_exp_f32_e32 v110, v33
	v_sub_f32_e32 v33, v122, v34
	v_add_f32_e32 v32, v90, v32
	v_exp_f32_e32 v112, v33
	v_sub_f32_e32 v33, v124, v34
	v_add_f32_e32 v32, v104, v32
	v_exp_f32_e32 v113, v33
	v_sub_f32_e32 v33, v125, v34
	v_add_f32_e32 v32, v107, v32
	v_exp_f32_e32 v114, v33
	v_add_f32_e32 v32, v110, v32
	v_exp_f32_e32 v45, v0
; __device__ __forceinline__ float shfl_idx(float v, int srclane) { return __int_as_float(__builtin_amdgcn_ds_bpermute(srclane << 2, __float_as_int(v))); }
; #define SBAR() __builtin_amdgcn_sched_barrier(0)
; __device__ __forceinline__ int v_st2(int k, int c) { const int kk = (k & ~0xC) | ((k & 4) << 1) | ((k & 8) >> 1); return ((kk >> 3) * 2 + (c >> 5)) * 512 + ((kk & 7) * 32 + (c & 31)) * 2; }
; __device__ __forceinline__ void dil_wave_item(const bf16* __restrict__ qkv, bf16* __restrict__ odil, float* __restrict__ lse,
;                               int pat, int g  , int head, char* wl  , const int W) {
;     ...
;   float ls = 0.f;
; #pragma unroll
;   for (int kb = 0; kb < 5; ++kb)
; #pragma unroll
;     for (int r = 0; r < 16; ++r) { const float e = __builtin_amdgcn_exp2f(sc[kb][r] - mx); sc[kb][r] = e; ls += e; }
;   ls += shfl_idx(ls, lane ^ 32);
;   f32x16 o0 = {}, o1 = {};
;   const int vb = (int)(uintptr_t)wl + v_rd_base(lane);
; #pragma unroll
;   for (int kb = 0; kb < 5; ++kb) {
;     bf16x8 vr[4];
; #pragma unroll
;     for (int i = 0; i < 4; ++i) {
;       const int key = i * 8 + (lane >> 3);
;       int kc = i0 - 64 + kb * 32 + key; kc = min(max(kc, 0), L - 1);
;       vr[i] = *reinterpret_cast<const bf16x8*>(qkv + (size_t)(tbase + kc * dil) * LDQ + 2560 + head * 64 + (lane & 7) * 8);
;     }
; #pragma unroll
;     for (int i = 0; i < 4; ++i) *reinterpret_cast<bf16x8*>(wl + v_st2(i * 8 + (lane >> 3), (lane & 7) * 8)) = vr[i];
;     bf16x8 pa0, pa1;
;     PK4(sc[kb], 0, pa0); PK4(sc[kb], 8, pa1);
;     asm volatile("s_waitcnt lgkmcnt(0)" ::: "memory");
;     const s16x4 a0 = tr_read<v_rd_off2(0, 0, 0)>(vb), b0 = tr_read<v_rd_off2(0, 0, 1)>(vb), a1 = tr_read<v_rd_off2(0, 1, 0)>(vb), b1 = tr_read<v_rd_off2(0, 1, 1)>(vb);
;     const s16x4 c0 = tr_read<v_rd_off2(1, 0, 0)>(vb), d0_ = tr_read<v_rd_off2(1, 0, 1)>(vb), c1 = tr_read<v_rd_off2(1, 1, 0)>(vb), d1 = tr_read<v_rd_off2(1, 1, 1)>(vb);
;     asm volatile("s_waitcnt lgkmcnt(0)" ::: "memory"); SBAR();
;     o0 = __builtin_amdgcn_mfma_f32_32x32x16_bf16(pa0, PKV(a0, b0), o0, 0, 0, 0);
;     o0 = __builtin_amdgcn_mfma_f32_32x32x16_bf16(pa1, PKV(a1, b1), o0, 0, 0, 0);
;     o1 = __builtin_amdgcn_mfma_f32_32x32x16_bf16(pa0, PKV(c0, d0_), o1, 0, 0, 0);
;     o1 = __builtin_amdgcn_mfma_f32_32x32x16_bf16(pa1, PKV(c1, d1), o1, 0, 0, 0);
	v_add_f32_e32 v32, v112, v32
	v_add_f32_e32 v32, v113, v32
	v_add_f32_e32 v32, v114, v32
	v_add_f32_e32 v0, v45, v32
	v_add_f32_e32 v0, v48, v0
	v_add_f32_e32 v0, v49, v0
	v_exp_f32_e32 v59, v1
	v_sub_f32_e32 v1, v7, v34
	v_add_f32_e32 v0, v52, v0
	v_exp_f32_e32 v63, v1
	v_sub_f32_e32 v1, v8, v34
	v_add_f32_e32 v0, v53, v0
	v_exp_f32_e32 v54, v1
	v_sub_f32_e32 v1, v9, v34
	v_add_f32_e32 v0, v56, v0
	v_exp_f32_e32 v57, v1
	v_sub_f32_e32 v1, v10, v34
	v_add_f32_e32 v0, v59, v0
	v_exp_f32_e32 v60, v1
	v_sub_f32_e32 v1, v11, v34
	v_add_f32_e32 v0, v63, v0
	v_exp_f32_e32 v64, v1
	v_sub_f32_e32 v1, v12, v34
	v_add_f32_e32 v0, v54, v0
	v_exp_f32_e32 v66, v1
	v_sub_f32_e32 v1, v13, v34
	v_add_f32_e32 v0, v57, v0
	v_exp_f32_e32 v69, v1
	v_sub_f32_e32 v1, v14, v34
	v_add_f32_e32 v0, v60, v0
	v_exp_f32_e32 v71, v1
	v_sub_f32_e32 v1, v15, v34
	v_add_f32_e32 v0, v64, v0
	v_exp_f32_e32 v72, v1
	v_add_f32_e32 v0, v66, v0
	v_add_f32_e32 v0, v69, v0
	v_add_f32_e32 v0, v71, v0
	v_lshlrev_b32_e32 v1, 4, v103
	v_add_f32_e32 v35, v72, v0
	v_lshlrev_b32_e32 v0, 3, v99
	v_and_b32_e32 v2, 0xc0, v1
	v_lshlrev_b32_e32 v3, 1, v103
	v_and_or_b32 v2, v0, 24, v2
	v_and_b32_e32 v3, 32, v3
	v_and_b32_e32 v0, 0x100, v0
	v_bfe_u32 v116, v103, 3, 3
	v_or3_b32 v0, v2, v3, v0
	v_or_b32_e32 v12, s41, v116
	v_add_u32_e32 v61, s55, v0
	v_subrev_u32_e32 v115, 64, v12
	v_lshlrev_b32_e32 v0, 3, v103
	v_and_b32_e32 v2, 56, v0
	v_bfe_u32 v117, v0, 5, 1
	v_max_i32_e32 v0, 0, v115
	v_min_u32_e32 v0, s15, v0
	v_subrev_u32_e32 v4, 56, v12
	v_lshlrev_b32_e32 v0, s40, v0
	v_max_i32_e32 v4, 0, v4
	v_add_u32_e32 v0, s42, v0
	v_min_u32_e32 v4, s15, v4
	v_subrev_u32_e32 v8, 48, v12
	v_and_b32_e32 v118, 48, v1
	v_mad_i64_i32 v[0:1], s[6:7], v0, s24, v[96:97]
	v_lshlrev_b32_e32 v4, s40, v4
	v_max_i32_e32 v8, 0, v8
	v_lshl_add_u64 v[0:1], v[0:1], 0, s[74:75]
	v_lshlrev_b32_e32 v32, 1, v2
	v_mov_b32_e32 v33, v95
	v_add_u32_e32 v4, s42, v4
	v_min_u32_e32 v8, s15, v8
	v_subrev_u32_e32 v12, 40, v12
	v_lshl_add_u64 v[0:1], v[0:1], 0, v[32:33]
	v_mad_i64_i32 v[4:5], s[6:7], v4, s24, v[96:97]
	v_lshlrev_b32_e32 v8, s40, v8
	v_max_i32_e32 v12, 0, v12
	v_add_co_u32_e32 v0, vcc, s25, v0
	v_lshl_add_u64 v[4:5], v[4:5], 0, s[74:75]
	v_add_u32_e32 v8, s42, v8
	v_min_u32_e32 v12, s15, v12
	v_addc_co_u32_e32 v1, vcc, 0, v1, vcc
	v_lshl_add_u64 v[4:5], v[4:5], 0, v[32:33]
	v_mad_i64_i32 v[8:9], s[6:7], v8, s24, v[96:97]
	v_lshlrev_b32_e32 v12, s40, v12
	v_add_co_u32_e32 v4, vcc, s25, v4
	v_lshl_add_u64 v[8:9], v[8:9], 0, s[74:75]
	v_add_u32_e32 v12, s42, v12
	v_addc_co_u32_e32 v5, vcc, 0, v5, vcc
	v_lshl_add_u64 v[8:9], v[8:9], 0, v[32:33]
	v_mad_i64_i32 v[12:13], s[6:7], v12, s24, v[96:97]
	global_load_dwordx4 v[0:3], v[0:1], off offset:1024
	v_add_co_u32_e32 v8, vcc, s25, v8
	v_lshl_add_u64 v[12:13], v[12:13], 0, s[74:75]
	s_nop 0
	v_addc_co_u32_e32 v9, vcc, 0, v9, vcc
	v_lshl_add_u64 v[12:13], v[12:13], 0, v[32:33]
	global_load_dwordx4 v[4:7], v[4:5], off offset:1024
	v_add_co_u32_e32 v12, vcc, s25, v12
	global_load_dwordx4 v[8:11], v[8:9], off offset:1024
	s_nop 0
	v_addc_co_u32_e32 v13, vcc, 0, v13, vcc
	global_load_dwordx4 v[12:15], v[12:13], off offset:1024
	v_lshrrev_b32_e32 v103, 4, v103
	v_and_or_b32 v103, v103, 2, v117
	v_lshlrev_b32_e32 v116, 6, v116
	s_movk_i32 s6, 0xc0
	v_and_or_b32 v117, v116, s6, v118
	v_lshl_add_u32 v103, v103, 9, s55
	v_add_u32_e32 v140, v103, v117
	s_movk_i32 s6, 0x100
	ds_bpermute_b32 v36, v126, v35
	s_waitcnt vmcnt(3)
	ds_write_b128 v140, v[0:3]
	v_or3_b32 v0, v116, v118, s6
	v_add_u32_e32 v103, v103, v0
	s_waitcnt vmcnt(2)
	ds_write_b128 v103, v[4:7]
	s_waitcnt vmcnt(1)
	ds_write_b128 v140, v[8:11] offset:2048
	s_waitcnt vmcnt(0)
	ds_write_b128 v103, v[12:15] offset:2048
	v_cvt_pk_bf16_f32 v16, v16, v17
	v_cvt_pk_bf16_f32 v17, v18, v19
	v_cvt_pk_bf16_f32 v18, v20, v21
	v_cvt_pk_bf16_f32 v19, v22, v23
	v_cvt_pk_bf16_f32 v116, v24, v25
	v_cvt_pk_bf16_f32 v117, v26, v27
	v_cvt_pk_bf16_f32 v118, v28, v29
	v_cvt_pk_bf16_f32 v119, v30, v31
	s_waitcnt lgkmcnt(0)
	ds_read_b64_tr_b16 v[0:1], v61 offset:0
	ds_read_b64_tr_b16 v[2:3], v61 offset:0x400
	ds_read_b64_tr_b16 v[20:21], v61 offset:0x800
	ds_read_b64_tr_b16 v[22:23], v61 offset:0xc00
	ds_read_b64_tr_b16 v[24:25], v61 offset:0x200
	ds_read_b64_tr_b16 v[26:27], v61 offset:0x600
	ds_read_b64_tr_b16 v[120:121], v61 offset:0xa00
	ds_read_b64_tr_b16 v[122:123], v61 offset:0xe00
	s_waitcnt lgkmcnt(0)
	s_nop 0
	v_permlane32_swap_b32_e32 v16, v18
	v_permlane32_swap_b32_e32 v17, v19
	v_permlane32_swap_b32_e32 v116, v118
	v_permlane32_swap_b32_e32 v117, v119
	v_mfma_f32_32x32x16_bf16 v[0:15], v[0:3], v[16:19], 0
	s_nop 0
	v_mfma_f32_32x32x16_bf16 v[0:15], v[20:23], v[116:119], v[0:15]
	v_mfma_f32_32x32x16_bf16 v[16:31], v[24:27], v[16:19], 0
	v_mfma_f32_32x32x16_bf16 v[16:31], v[120:123], v[116:119], v[16:31]
	v_max_i32_e32 v116, 0xffffffe0, v115
	v_add_u32_e32 v116, 32, v116
	v_min_u32_e32 v116, s15, v116
	v_max_i32_e32 v118, 0xffffffd8, v115
	v_lshlrev_b32_e32 v116, s40, v116
	v_add_u32_e32 v118, 40, v118
	v_add_u32_e32 v116, s42, v116
	v_min_u32_e32 v118, s15, v118
	v_max_i32_e32 v124, 0xffffffd0, v115
	v_mad_i64_i32 v[116:117], s[6:7], v116, s24, v[96:97]
	v_lshlrev_b32_e32 v118, s40, v118
	v_add_u32_e32 v124, 48, v124
	v_lshl_add_u64 v[116:117], v[116:117], 0, s[74:75]
	v_add_u32_e32 v118, s42, v118
	v_min_u32_e32 v124, s15, v124
	v_max_i32_e32 v126, 0xffffffc8, v115
	v_lshl_add_u64 v[116:117], v[116:117], 0, v[32:33]
	v_mad_i64_i32 v[118:119], s[6:7], v118, s24, v[96:97]
	v_lshlrev_b32_e32 v124, s40, v124
	v_add_u32_e32 v126, 56, v126
	v_add_co_u32_e32 v116, vcc, s25, v116
	v_lshl_add_u64 v[118:119], v[118:119], 0, s[74:75]
	v_add_u32_e32 v124, s42, v124
	v_min_u32_e32 v126, s15, v126
	v_addc_co_u32_e32 v117, vcc, 0, v117, vcc
	v_lshl_add_u64 v[118:119], v[118:119], 0, v[32:33]
	v_mad_i64_i32 v[124:125], s[6:7], v124, s24, v[96:97]
	v_lshlrev_b32_e32 v126, s40, v126
	v_add_co_u32_e32 v120, vcc, s25, v118
	v_lshl_add_u64 v[124:125], v[124:125], 0, s[74:75]
	v_add_u32_e32 v126, s42, v126
	v_addc_co_u32_e32 v121, vcc, 0, v119, vcc
	v_lshl_add_u64 v[124:125], v[124:125], 0, v[32:33]
	v_mad_i64_i32 v[126:127], s[6:7], v126, s24, v[96:97]
	v_add_co_u32_e32 v124, vcc, s25, v124
	v_lshl_add_u64 v[126:127], v[126:127], 0, s[74:75]
	s_nop 0
	v_addc_co_u32_e32 v125, vcc, 0, v125, vcc
	v_lshl_add_u64 v[126:127], v[126:127], 0, v[32:33]
	v_add_co_u32_e32 v128, vcc, s25, v126
	global_load_dwordx4 v[116:119], v[116:117], off offset:1024
	s_nop 0
	global_load_dwordx4 v[120:123], v[120:121], off offset:1024
	v_addc_co_u32_e32 v129, vcc, 0, v127, vcc
	global_load_dwordx4 v[124:127], v[124:125], off offset:1024
	s_nop 0
	global_load_dwordx4 v[128:131], v[128:129], off offset:1024
	s_waitcnt vmcnt(3)
; #define SBAR() __builtin_amdgcn_sched_barrier(0)
; __device__ __forceinline__ int v_st2(int k, int c) { const int kk = (k & ~0xC) | ((k & 4) << 1) | ((k & 8) >> 1); return ((kk >> 3) * 2 + (c >> 5)) * 512 + ((kk & 7) * 32 + (c & 31)) * 2; }
; __device__ __forceinline__ void dil_wave_item(const bf16* __restrict__ qkv, bf16* __restrict__ odil, float* __restrict__ lse,
;                               int pat, int g  , int head, char* wl  , const int W) {
;     ...
;   for (int kb = 0; kb < 5; ++kb) {
;     bf16x8 vr[4];
; #pragma unroll
;     for (int i = 0; i < 4; ++i) {
;       const int key = i * 8 + (lane >> 3);
;       int kc = i0 - 64 + kb * 32 + key; kc = min(max(kc, 0), L - 1);
;       vr[i] = *reinterpret_cast<const bf16x8*>(qkv + (size_t)(tbase + kc * dil) * LDQ + 2560 + head * 64 + (lane & 7) * 8);
;     }
; #pragma unroll
;     for (int i = 0; i < 4; ++i) *reinterpret_cast<bf16x8*>(wl + v_st2(i * 8 + (lane >> 3), (lane & 7) * 8)) = vr[i];
;     bf16x8 pa0, pa1;
;     PK4(sc[kb], 0, pa0); PK4(sc[kb], 8, pa1);
;     asm volatile("s_waitcnt lgkmcnt(0)" ::: "memory");
;     const s16x4 a0 = tr_read<v_rd_off2(0, 0, 0)>(vb), b0 = tr_read<v_rd_off2(0, 0, 1)>(vb), a1 = tr_read<v_rd_off2(0, 1, 0)>(vb), b1 = tr_read<v_rd_off2(0, 1, 1)>(vb);
;     const s16x4 c0 = tr_read<v_rd_off2(1, 0, 0)>(vb), d0_ = tr_read<v_rd_off2(1, 0, 1)>(vb), c1 = tr_read<v_rd_off2(1, 1, 0)>(vb), d1 = tr_read<v_rd_off2(1, 1, 1)>(vb);
;     asm volatile("s_waitcnt lgkmcnt(0)" ::: "memory"); SBAR();
;     o0 = __builtin_amdgcn_mfma_f32_32x32x16_bf16(pa0, PKV(a0, b0), o0, 0, 0, 0);
;     o0 = __builtin_amdgcn_mfma_f32_32x32x16_bf16(pa1, PKV(a1, b1), o0, 0, 0, 0);
;     o1 = __builtin_amdgcn_mfma_f32_32x32x16_bf16(pa0, PKV(c0, d0_), o1, 0, 0, 0);
;     o1 = __builtin_amdgcn_mfma_f32_32x32x16_bf16(pa1, PKV(c1, d1), o1, 0, 0, 0);
;     SBAR();
	ds_write_b128 v140, v[116:119]
	s_waitcnt vmcnt(2)
	ds_write_b128 v103, v[120:123]
	s_waitcnt vmcnt(1)
	ds_write_b128 v140, v[124:127] offset:2048
	s_waitcnt vmcnt(0)
	ds_write_b128 v103, v[128:131] offset:2048
	v_cvt_pk_bf16_f32 v116, v37, v38
	v_cvt_pk_bf16_f32 v117, v39, v41
	v_cvt_pk_bf16_f32 v118, v44, v50
	v_cvt_pk_bf16_f32 v119, v55, v65
	v_cvt_pk_bf16_f32 v120, v68, v73
	v_cvt_pk_bf16_f32 v121, v76, v81
	v_cvt_pk_bf16_f32 v122, v86, v89
	v_cvt_pk_bf16_f32 v123, v91, v106
	s_waitcnt lgkmcnt(0)
	ds_read_b64_tr_b16 v[124:125], v61 offset:0
	ds_read_b64_tr_b16 v[126:127], v61 offset:0x400
	ds_read_b64_tr_b16 v[128:129], v61 offset:0x800
	ds_read_b64_tr_b16 v[130:131], v61 offset:0xc00
	ds_read_b64_tr_b16 v[132:133], v61 offset:0x200
	ds_read_b64_tr_b16 v[134:135], v61 offset:0x600
	ds_read_b64_tr_b16 v[136:137], v61 offset:0xa00
	ds_read_b64_tr_b16 v[138:139], v61 offset:0xe00
	s_waitcnt lgkmcnt(0)
	s_nop 0
	v_permlane32_swap_b32_e32 v116, v118
	v_permlane32_swap_b32_e32 v117, v119
	v_permlane32_swap_b32_e32 v120, v122
	v_permlane32_swap_b32_e32 v121, v123
	v_mfma_f32_32x32x16_bf16 v[0:15], v[124:127], v[116:119], v[0:15]
	v_mfma_f32_32x32x16_bf16 v[16:31], v[132:135], v[116:119], v[16:31]
	v_mfma_f32_32x32x16_bf16 v[0:15], v[128:131], v[120:123], v[0:15]
	v_mfma_f32_32x32x16_bf16 v[16:31], v[136:139], v[120:123], v[16:31]
	v_max_i32_e32 v37, 0xffffffc0, v115
	v_add_u32_e32 v37, 64, v37
	v_min_u32_e32 v37, s15, v37
	v_lshlrev_b32_e32 v37, s40, v37
	v_add_u32_e32 v37, s42, v37
	v_mad_i64_i32 v[38:39], s[6:7], v37, s24, v[96:97]
	v_max_i32_e32 v37, 0xffffffb8, v115
	v_add_u32_e32 v37, 0x48, v37
	v_min_u32_e32 v37, s15, v37
	v_lshlrev_b32_e32 v37, s40, v37
	v_lshl_add_u64 v[38:39], v[38:39], 0, s[74:75]
	v_add_u32_e32 v37, s42, v37
	v_lshl_add_u64 v[38:39], v[38:39], 0, v[32:33]
	v_mad_i64_i32 v[116:117], s[6:7], v37, s24, v[96:97]
	v_max_i32_e32 v37, 0xffffffb0, v115
	v_add_co_u32_e32 v38, vcc, s25, v38
	v_lshl_add_u64 v[116:117], v[116:117], 0, s[74:75]
	v_add_u32_e32 v37, 0x50, v37
	v_addc_co_u32_e32 v39, vcc, 0, v39, vcc
	v_lshl_add_u64 v[116:117], v[116:117], 0, v[32:33]
	v_min_u32_e32 v37, s15, v37
	v_add_co_u32_e32 v120, vcc, s25, v116
	v_lshlrev_b32_e32 v37, s40, v37
	s_nop 0
	v_addc_co_u32_e32 v121, vcc, 0, v117, vcc
	v_add_u32_e32 v37, s42, v37
	global_load_dwordx4 v[116:119], v[38:39], off offset:1024
	s_nop 0
	global_load_dwordx4 v[120:123], v[120:121], off offset:1024
	v_mad_i64_i32 v[38:39], s[6:7], v37, s24, v[96:97]
	v_max_i32_e32 v37, 0xffffffa8, v115
	v_add_u32_e32 v37, 0x58, v37
	v_min_u32_e32 v37, s15, v37
	v_lshlrev_b32_e32 v37, s40, v37
	v_lshl_add_u64 v[38:39], v[38:39], 0, s[74:75]
	v_add_u32_e32 v37, s42, v37
	v_lshl_add_u64 v[38:39], v[38:39], 0, v[32:33]
	v_mad_i64_i32 v[124:125], s[6:7], v37, s24, v[96:97]
	v_add_co_u32_e32 v38, vcc, s25, v38
	v_lshl_add_u64 v[124:125], v[124:125], 0, s[74:75]
	s_nop 0
	v_addc_co_u32_e32 v39, vcc, 0, v39, vcc
	v_lshl_add_u64 v[124:125], v[124:125], 0, v[32:33]
	v_add_co_u32_e32 v128, vcc, s25, v124
	s_nop 1
	v_addc_co_u32_e32 v129, vcc, 0, v125, vcc
	global_load_dwordx4 v[124:127], v[38:39], off offset:1024
	s_nop 0
	global_load_dwordx4 v[128:131], v[128:129], off offset:1024
	s_waitcnt vmcnt(3)
	ds_write_b128 v140, v[116:119]
	s_waitcnt vmcnt(2)
	ds_write_b128 v103, v[120:123]
	s_waitcnt vmcnt(1)
	ds_write_b128 v140, v[124:127] offset:2048
	s_waitcnt vmcnt(0)
	ds_write_b128 v103, v[128:131] offset:2048
	v_cvt_pk_bf16_f32 v38, v40, v42
	v_cvt_pk_bf16_f32 v39, v43, v47
	v_cvt_pk_bf16_f32 v40, v62, v70
	v_cvt_pk_bf16_f32 v41, v74, v77
	v_cvt_pk_bf16_f32 v116, v78, v82
	v_cvt_pk_bf16_f32 v117, v84, v88
	v_cvt_pk_bf16_f32 v118, v105, v108
	v_cvt_pk_bf16_f32 v119, v109, v111
	s_waitcnt lgkmcnt(0)
	ds_read_b64_tr_b16 v[120:121], v61 offset:0
	ds_read_b64_tr_b16 v[122:123], v61 offset:0x400
	ds_read_b64_tr_b16 v[124:125], v61 offset:0x800
	ds_read_b64_tr_b16 v[126:127], v61 offset:0xc00
	ds_read_b64_tr_b16 v[128:129], v61 offset:0x200
	ds_read_b64_tr_b16 v[130:131], v61 offset:0x600
	ds_read_b64_tr_b16 v[132:133], v61 offset:0xa00
	ds_read_b64_tr_b16 v[134:135], v61 offset:0xe00
	s_waitcnt lgkmcnt(0)
	s_nop 0
	v_permlane32_swap_b32_e32 v38, v40
	v_permlane32_swap_b32_e32 v39, v41
	v_permlane32_swap_b32_e32 v116, v118
	v_permlane32_swap_b32_e32 v117, v119
	v_mfma_f32_32x32x16_bf16 v[0:15], v[120:123], v[38:41], v[0:15]
	v_mfma_f32_32x32x16_bf16 v[16:31], v[128:131], v[38:41], v[16:31]
	v_mfma_f32_32x32x16_bf16 v[0:15], v[124:127], v[116:119], v[0:15]
	v_mfma_f32_32x32x16_bf16 v[16:31], v[132:135], v[116:119], v[16:31]
	v_max_i32_e32 v37, 0xffffffa0, v115
	v_add_u32_e32 v37, 0x60, v37
	v_min_u32_e32 v37, s15, v37
	v_lshlrev_b32_e32 v37, s40, v37
	v_add_u32_e32 v37, s42, v37
	v_mad_i64_i32 v[38:39], s[6:7], v37, s24, v[96:97]
	v_max_i32_e32 v37, 0xffffff98, v115
	v_add_u32_e32 v37, 0x68, v37
	v_min_u32_e32 v37, s15, v37
	v_lshlrev_b32_e32 v37, s40, v37
	v_lshl_add_u64 v[38:39], v[38:39], 0, s[74:75]
	v_add_u32_e32 v37, s42, v37
	v_lshl_add_u64 v[38:39], v[38:39], 0, v[32:33]
	v_mad_i64_i32 v[40:41], s[6:7], v37, s24, v[96:97]
	v_max_i32_e32 v37, 0xffffff90, v115
	v_add_co_u32_e32 v38, vcc, s25, v38
	v_lshl_add_u64 v[40:41], v[40:41], 0, s[74:75]
	v_add_u32_e32 v37, 0x70, v37
	v_addc_co_u32_e32 v39, vcc, 0, v39, vcc
	v_lshl_add_u64 v[40:41], v[40:41], 0, v[32:33]
	v_min_u32_e32 v37, s15, v37
	v_add_co_u32_e32 v42, vcc, s25, v40
	v_lshlrev_b32_e32 v37, s40, v37
	s_nop 0
	v_addc_co_u32_e32 v43, vcc, 0, v41, vcc
	v_add_u32_e32 v37, s42, v37
	global_load_dwordx4 v[38:41], v[38:39], off offset:1024
	s_nop 0
	global_load_dwordx4 v[116:119], v[42:43], off offset:1024
	v_mad_i64_i32 v[42:43], s[6:7], v37, s24, v[96:97]
	v_max_i32_e32 v37, 0xffffff88, v115
	v_add_u32_e32 v37, 0x78, v37
	v_min_u32_e32 v37, s15, v37
	v_lshlrev_b32_e32 v37, s40, v37
	v_lshl_add_u64 v[42:43], v[42:43], 0, s[74:75]
	v_add_u32_e32 v37, s42, v37
	v_lshl_add_u64 v[42:43], v[42:43], 0, v[32:33]
	v_mad_i64_i32 v[76:77], s[6:7], v37, s24, v[96:97]
	v_add_co_u32_e32 v42, vcc, s25, v42
	v_lshl_add_u64 v[76:77], v[76:77], 0, s[74:75]
	s_nop 0
	v_addc_co_u32_e32 v43, vcc, 0, v43, vcc
	v_lshl_add_u64 v[76:77], v[76:77], 0, v[32:33]
	v_add_co_u32_e32 v76, vcc, s25, v76
	s_nop 1
	v_addc_co_u32_e32 v77, vcc, 0, v77, vcc
	global_load_dwordx4 v[120:123], v[42:43], off offset:1024
	global_load_dwordx4 v[124:127], v[76:77], off offset:1024
	s_waitcnt vmcnt(3)
; #define SBAR() __builtin_amdgcn_sched_barrier(0)
; __device__ __forceinline__ int v_st2(int k, int c) { const int kk = (k & ~0xC) | ((k & 4) << 1) | ((k & 8) >> 1); return ((kk >> 3) * 2 + (c >> 5)) * 512 + ((kk & 7) * 32 + (c & 31)) * 2; }
; __device__ __forceinline__ void dil_wave_item(const bf16* __restrict__ qkv, bf16* __restrict__ odil, float* __restrict__ lse,
;                               int pat, int g  , int head, char* wl  , const int W) {
;     ...
;   for (int kb = 0; kb < 5; ++kb) {
;     bf16x8 vr[4];
; #pragma unroll
;     for (int i = 0; i < 4; ++i) {
;       const int key = i * 8 + (lane >> 3);
;       int kc = i0 - 64 + kb * 32 + key; kc = min(max(kc, 0), L - 1);
;       vr[i] = *reinterpret_cast<const bf16x8*>(qkv + (size_t)(tbase + kc * dil) * LDQ + 2560 + head * 64 + (lane & 7) * 8);
;     }
; #pragma unroll
;     for (int i = 0; i < 4; ++i) *reinterpret_cast<bf16x8*>(wl + v_st2(i * 8 + (lane >> 3), (lane & 7) * 8)) = vr[i];
;     bf16x8 pa0, pa1;
;     PK4(sc[kb], 0, pa0); PK4(sc[kb], 8, pa1);
;     asm volatile("s_waitcnt lgkmcnt(0)" ::: "memory");
;     const s16x4 a0 = tr_read<v_rd_off2(0, 0, 0)>(vb), b0 = tr_read<v_rd_off2(0, 0, 1)>(vb), a1 = tr_read<v_rd_off2(0, 1, 0)>(vb), b1 = tr_read<v_rd_off2(0, 1, 1)>(vb);
;     const s16x4 c0 = tr_read<v_rd_off2(1, 0, 0)>(vb), d0_ = tr_read<v_rd_off2(1, 0, 1)>(vb), c1 = tr_read<v_rd_off2(1, 1, 0)>(vb), d1 = tr_read<v_rd_off2(1, 1, 1)>(vb);
;     asm volatile("s_waitcnt lgkmcnt(0)" ::: "memory"); SBAR();
;     o0 = __builtin_amdgcn_mfma_f32_32x32x16_bf16(pa0, PKV(a0, b0), o0, 0, 0, 0);
;     o0 = __builtin_amdgcn_mfma_f32_32x32x16_bf16(pa1, PKV(a1, b1), o0, 0, 0, 0);
;     o1 = __builtin_amdgcn_mfma_f32_32x32x16_bf16(pa0, PKV(c0, d0_), o1, 0, 0, 0);
;     o1 = __builtin_amdgcn_mfma_f32_32x32x16_bf16(pa1, PKV(c1, d1), o1, 0, 0, 0);
;     SBAR();
;   }
;   if (hi == 0) lse[((size_t)pat * T + tbase + (i0 + r32) * dil) * 8 + head] = mx + __log2f(ls);
	ds_write_b128 v140, v[38:41]
	s_waitcnt vmcnt(2)
	ds_write_b128 v103, v[116:119]
	s_waitcnt vmcnt(1)
	ds_write_b128 v140, v[120:123] offset:2048
	s_waitcnt vmcnt(0)
	ds_write_b128 v103, v[124:127] offset:2048
	v_cvt_pk_bf16_f32 v38, v46, v51
	v_cvt_pk_bf16_f32 v39, v58, v67
	v_cvt_pk_bf16_f32 v40, v75, v79
	v_cvt_pk_bf16_f32 v41, v83, v85
	v_cvt_pk_bf16_f32 v74, v87, v90
	v_cvt_pk_bf16_f32 v75, v104, v107
	v_cvt_pk_bf16_f32 v76, v110, v112
	v_cvt_pk_bf16_f32 v77, v113, v114
	s_waitcnt lgkmcnt(0)
	ds_read_b64_tr_b16 v[82:83], v61 offset:0
	ds_read_b64_tr_b16 v[84:85], v61 offset:0x400
	ds_read_b64_tr_b16 v[86:87], v61 offset:0x800
	ds_read_b64_tr_b16 v[88:89], v61 offset:0xc00
	ds_read_b64_tr_b16 v[104:105], v61 offset:0x200
	ds_read_b64_tr_b16 v[106:107], v61 offset:0x600
	ds_read_b64_tr_b16 v[108:109], v61 offset:0xa00
	ds_read_b64_tr_b16 v[110:111], v61 offset:0xe00
	s_waitcnt lgkmcnt(0)
	s_nop 0
	v_permlane32_swap_b32_e32 v38, v40
	v_permlane32_swap_b32_e32 v39, v41
	v_permlane32_swap_b32_e32 v74, v76
	v_permlane32_swap_b32_e32 v75, v77
	v_mfma_f32_32x32x16_bf16 v[0:15], v[82:85], v[38:41], v[0:15]
	v_mfma_f32_32x32x16_bf16 v[16:31], v[104:107], v[38:41], v[16:31]
	v_mfma_f32_32x32x16_bf16 v[0:15], v[86:89], v[74:77], v[0:15]
	v_mfma_f32_32x32x16_bf16 v[16:31], v[108:111], v[74:77], v[16:31]
	v_max_i32_e32 v37, 0xffffff80, v115
	v_add_u32_e32 v37, 0x80, v37
	v_min_u32_e32 v37, s15, v37
	v_lshlrev_b32_e32 v37, s40, v37
	v_add_u32_e32 v37, s42, v37
	v_mad_i64_i32 v[38:39], s[6:7], v37, s24, v[96:97]
	v_max_i32_e32 v37, 0xffffff78, v115
	v_add_u32_e32 v37, 0x88, v37
	v_min_u32_e32 v37, s15, v37
	v_lshlrev_b32_e32 v37, s40, v37
	v_lshl_add_u64 v[38:39], v[38:39], 0, s[74:75]
	v_add_u32_e32 v37, s42, v37
	v_lshl_add_u64 v[38:39], v[38:39], 0, v[32:33]
	v_mad_i64_i32 v[40:41], s[6:7], v37, s24, v[96:97]
	v_max_i32_e32 v37, 0xffffff70, v115
	v_add_co_u32_e32 v38, vcc, s25, v38
	v_lshl_add_u64 v[40:41], v[40:41], 0, s[74:75]
	v_add_u32_e32 v37, 0x90, v37
	v_addc_co_u32_e32 v39, vcc, 0, v39, vcc
	v_lshl_add_u64 v[40:41], v[40:41], 0, v[32:33]
	v_min_u32_e32 v37, s15, v37
	v_add_co_u32_e32 v42, vcc, s25, v40
	v_lshlrev_b32_e32 v37, s40, v37
	s_nop 0
	v_addc_co_u32_e32 v43, vcc, 0, v41, vcc
	v_add_u32_e32 v37, s42, v37
	global_load_dwordx4 v[38:41], v[38:39], off offset:1024
	s_nop 0
	global_load_dwordx4 v[74:77], v[42:43], off offset:1024
	v_mad_i64_i32 v[42:43], s[6:7], v37, s24, v[96:97]
	v_max_i32_e32 v37, 0xffffff68, v115
	v_add_u32_e32 v37, 0x98, v37
	v_min_u32_e32 v37, s15, v37
	v_lshlrev_b32_e32 v37, s40, v37
	v_lshl_add_u64 v[42:43], v[42:43], 0, s[74:75]
	v_add_u32_e32 v37, s42, v37
	v_lshl_add_u64 v[42:43], v[42:43], 0, v[32:33]
	v_mad_i64_i32 v[46:47], s[6:7], v37, s24, v[96:97]
	v_add_co_u32_e32 v42, vcc, s25, v42
	v_lshl_add_u64 v[46:47], v[46:47], 0, s[74:75]
	s_nop 0
	v_addc_co_u32_e32 v43, vcc, 0, v43, vcc
	v_lshl_add_u64 v[32:33], v[46:47], 0, v[32:33]
	v_add_co_u32_e32 v32, vcc, s25, v32
	s_nop 1
	v_addc_co_u32_e32 v33, vcc, 0, v33, vcc
	global_load_dwordx4 v[82:85], v[42:43], off offset:1024
	global_load_dwordx4 v[86:89], v[32:33], off offset:1024
	s_waitcnt vmcnt(3)
	ds_write_b128 v140, v[38:41]
	s_waitcnt vmcnt(2)
	ds_write_b128 v103, v[74:77]
	s_waitcnt vmcnt(1)
	ds_write_b128 v140, v[82:85] offset:2048
	s_waitcnt vmcnt(0)
	ds_write_b128 v103, v[86:89] offset:2048
	v_cvt_pk_bf16_f32 v38, v45, v48
	v_cvt_pk_bf16_f32 v39, v49, v52
	v_cvt_pk_bf16_f32 v40, v53, v56
	v_cvt_pk_bf16_f32 v41, v59, v63
	v_cvt_pk_bf16_f32 v42, v54, v57
	v_cvt_pk_bf16_f32 v43, v60, v64
	v_cvt_pk_bf16_f32 v44, v66, v69
	v_cvt_pk_bf16_f32 v45, v71, v72
	s_waitcnt lgkmcnt(0)
	ds_read_b64_tr_b16 v[46:47], v61 offset:0
	ds_read_b64_tr_b16 v[48:49], v61 offset:0x400
	ds_read_b64_tr_b16 v[50:51], v61 offset:0x800
	ds_read_b64_tr_b16 v[52:53], v61 offset:0xc00
	ds_read_b64_tr_b16 v[54:55], v61 offset:0x200
	ds_read_b64_tr_b16 v[56:57], v61 offset:0x600
	ds_read_b64_tr_b16 v[62:63], v61 offset:0xa00
	ds_read_b64_tr_b16 v[64:65], v61 offset:0xe00
	s_waitcnt lgkmcnt(0)
	s_nop 0
	v_permlane32_swap_b32_e32 v38, v40
	v_permlane32_swap_b32_e32 v39, v41
	v_permlane32_swap_b32_e32 v42, v44
	v_permlane32_swap_b32_e32 v43, v45
	v_mfma_f32_32x32x16_bf16 v[0:15], v[46:49], v[38:41], v[0:15]
	v_mfma_f32_32x32x16_bf16 v[16:31], v[54:57], v[38:41], v[16:31]
	v_mfma_f32_32x32x16_bf16 v[0:15], v[50:53], v[42:45], v[0:15]
	v_mfma_f32_32x32x16_bf16 v[16:31], v[62:65], v[42:45], v[16:31]
	v_cmp_lt_u32_e32 vcc, 31, v99
	s_and_saveexec_b64 s[6:7], vcc
	s_xor_b64 s[6:7], exec, s[6:7]
	s_ashr_i32 s15, s14, 31
	s_lshl_b64 s[8:9], s[14:15], 15
	s_ashr_i32 s15, s42, 31
	s_add_u32 s20, s8, s42
	s_addc_u32 s21, s9, s15
	s_or_saveexec_b64 s[6:7], s[6:7]
	s_waitcnt lgkmcnt(14)
	v_add_f32_e32 v35, v35, v36
	v_mov_b64_e32 v[32:33], s[20:21]
	s_xor_b64 exec, exec, s[6:7]
	s_cbranch_execz .LBB0_293
	v_log_f32_e32 v32, v35
	s_ashr_i32 s15, s14, 31
	s_lshl_b64 s[8:9], s[14:15], 15
	s_ashr_i32 s14, s42, 31
	s_add_u32 s8, s8, s42
	s_addc_u32 s9, s9, s14
	v_ashrrev_i32_e32 v99, 31, v98
	v_add_f32_e32 v34, v34, v32
	v_lshl_add_u64 v[32:33], s[8:9], 0, v[98:99]
	v_lshlrev_b64 v[32:33], 5, v[32:33]
	v_lshl_add_u64 v[32:33], s[72:73], 0, v[32:33]
	global_store_dword v[32:33], v34, off
	v_mov_b64_e32 v[32:33], s[8:9]
	s_branch .LBB0_293
